# P5/P12 epilogue math with packed f32 ops (v_pk_fma/mul/add) where both halves share an operation
# speedup vs baseline: 1.0152x; 1.0043x over previous
; DEV float silu_f(float x) { return x * __builtin_amdgcn_rcpf(1.f + __expf(-x)); }
; DEV float gelu_f(float x) { const float t = 1.5957691216f * (x + 0.044715f * x * x * x); return x * __builtin_amdgcn_rcpf(1.f + __expf(-t)); }
; DEV u32x4 pack8(const float (&f)[8]) { u32x4 w; w.x = cvt_pk_bf16(f[0], f[1]); w.y = cvt_pk_bf16(f[2], f[3]); w.z = cvt_pk_bf16(f[4], f[5]); w.w = cvt_pk_bf16(f[6], f[7]); return w; }
;     DEV void operator()(const f32x4 (&acc)[2][2][4][2], const Unit& u, int wr, int wc, int fr, int fq) const {
;     ...
;         const int pn = u.pn; const int act = (pn < 4 || pn >= 10) ? 0 : (pn < 6 ? 1 : 2); const bool stat = (pn == 8 || pn == 9);
;         const int row0 = u.pm * 256 + wr * 64 + fr, col0 = pn * 256 + wc * 32 + 8 * fq; const int b = u.pm < MLAT / 256 ? (u.pm >> 4) : 16;
;         f32x4 sw[2][2];
; #pragma unroll
;         for (int bj = 0; bj < 2; ++bj)
; #pragma unroll
;             for (int n = 0; n < 2; ++n) sw[bj][n] = *(const f32x4*)(shw + (size_t)b * ZW + col0 + bj * 128 + 4 * n);
;         float rstd8[8]; row_rstd8(rs, row0, fq, rstd8);
; #pragma unroll
;         for (int ai = 0; ai < 2; ++ai)
; #pragma unroll
;             for (int m = 0; m < 4; ++m) {
;                 const int row = row0 + ai * 128 + m * 16; float ss = 0.f; const float rstd = rstd8[ai * 4 + m];
; #pragma unroll
;                 for (int bj = 0; bj < 2; ++bj) {
;                     float v[8];
; #pragma unroll
;                     for (int n = 0; n < 2; ++n)
; #pragma unroll
;                         for (int j = 0; j < 4; ++j) { float x = acc[ai][bj][m][n][j] * rstd + sw[bj][n][j]; if (act == 1) x = silu_f(x); else if (act == 2) x = gelu_f(x); v[4 * n + j] = x; ss += x * x; }
;                     *(u32x4*)(Z + (size_t)row * ZW + col0 + bj * 128) = pack8(v);
.LBB0_484:
	s_waitcnt vmcnt(8)
	v_mov_b32_e32 v174, 0x358637bd
	s_mov_b32 s7, 0x3a800000
	v_fma_f32 v243, v243, s7, v174
	v_fma_f32 v244, v244, s7, v174
	v_fma_f32 v245, v245, s7, v174
	v_fma_f32 v246, v246, s7, v174
	v_fma_f32 v247, v247, s7, v174
	v_fma_f32 v248, v248, s7, v174
	v_fma_f32 v249, v249, s7, v174
	v_fma_f32 v250, v250, s7, v174
	v_rsq_f32_e32 v243, v243
	v_rsq_f32_e32 v244, v244
	v_rsq_f32_e32 v245, v245
	v_rsq_f32_e32 v246, v246
	v_rsq_f32_e32 v247, v247
	v_rsq_f32_e32 v248, v248
	v_rsq_f32_e32 v249, v249
	v_rsq_f32_e32 v250, v250
	s_lshl_b32 s11, s73, 4
	s_lshl_b32 s7, s74, 3
	s_add_u32 s11, s11, s7
	s_add_u32 s11, s11, 0x20000
	v_lshl_add_u32 v175, v204, 2, s11
	ds_write_b32 v175, v251
	v_lshl_add_u32 v176, v165, 5, s11
	s_lshl_b32 s12, s6, 8
	s_add_u32 s12, s12, s73
	s_lshl_b32 s7, s10, 8
	s_or_b32 s7, s7, s74
	v_add_u32_e32 v177, s12, v147
	v_mul_u32_u24_e32 v178, 0x1600, v177
	v_lshl_add_u32 v179, v165, 3, s7
	v_lshl_add_u32 v178, v179, 1, v178
	s_add_u32 s48, s88, 0xc800000
	s_addc_u32 s49, s89, 0
	s_mov_b32 s32, 0x3d372713
	v_mov_b32_e32 v183, 0
	v_mov_b32_e32 v184, 0
	v_mov_b32_e32 v185, 0
	v_mov_b32_e32 v186, 0
	v_mov_b32_e32 v187, 0
	v_mov_b32_e32 v188, 0
	v_mov_b32_e32 v189, 0
	v_mov_b32_e32 v190, 0
	s_waitcnt lgkmcnt(0)
	ds_read_b128 v[22:25], v176
	ds_read_b128 v[30:33], v176 offset:16
	ds_read_b128 v[38:41], v176 offset:128
	ds_read_b128 v[46:49], v176 offset:144
	s_waitcnt lgkmcnt(0)
	s_cmp_lt_i32 s10, 4
	s_cbranch_scc1 .Lp5_act0
	s_cmp_gt_i32 s10, 9
	s_cbranch_scc1 .Lp5_act0
	s_cmp_lt_i32 s10, 6
	s_cbranch_scc1 .Lp5_act1
.Lp5_act2:
	s_mov_b32 s100, 0xc0135761
	v_pk_fma_f32 v[142:143], v[142:143], v[242:243], v[22:23] op_sel:[0,1,0]
	v_pk_fma_f32 v[144:145], v[144:145], v[242:243], v[24:25] op_sel:[0,1,0]
	v_pk_fma_f32 v[138:139], v[138:139], v[242:243], v[30:31] op_sel:[0,1,0]
	v_pk_fma_f32 v[140:141], v[140:141], v[242:243], v[32:33] op_sel:[0,1,0]
	v_pk_mul_f32 v[166:167], v[142:143], v[142:143]
	v_pk_mul_f32 v[168:169], v[144:145], v[144:145]
	v_pk_mul_f32 v[170:171], v[138:139], v[138:139]
	v_pk_mul_f32 v[172:173], v[140:141], v[140:141]
	v_pk_fma_f32 v[166:167], v[166:167], s[32:33], 1.0 op_sel_hi:[1,0,0]
	v_pk_fma_f32 v[168:169], v[168:169], s[32:33], 1.0 op_sel_hi:[1,0,0]
	v_pk_fma_f32 v[170:171], v[170:171], s[32:33], 1.0 op_sel_hi:[1,0,0]
	v_pk_fma_f32 v[172:173], v[172:173], s[32:33], 1.0 op_sel_hi:[1,0,0]
	v_pk_mul_f32 v[166:167], v[166:167], v[142:143]
	v_pk_mul_f32 v[168:169], v[168:169], v[144:145]
	v_pk_mul_f32 v[170:171], v[170:171], v[138:139]
	v_pk_mul_f32 v[172:173], v[172:173], v[140:141]
	v_pk_mul_f32 v[166:167], v[166:167], s[100:101] op_sel_hi:[1,0]
	v_pk_mul_f32 v[168:169], v[168:169], s[100:101] op_sel_hi:[1,0]
	v_pk_mul_f32 v[170:171], v[170:171], s[100:101] op_sel_hi:[1,0]
	v_pk_mul_f32 v[172:173], v[172:173], s[100:101] op_sel_hi:[1,0]
	v_exp_f32_e32 v166, v166
	v_exp_f32_e32 v167, v167
	v_exp_f32_e32 v168, v168
	v_exp_f32_e32 v169, v169
	v_exp_f32_e32 v170, v170
	v_exp_f32_e32 v171, v171
	v_exp_f32_e32 v172, v172
	v_exp_f32_e32 v173, v173
	v_pk_add_f32 v[166:167], v[166:167], 1.0 op_sel_hi:[1,0]
	v_pk_add_f32 v[168:169], v[168:169], 1.0 op_sel_hi:[1,0]
	v_pk_add_f32 v[170:171], v[170:171], 1.0 op_sel_hi:[1,0]
	v_pk_add_f32 v[172:173], v[172:173], 1.0 op_sel_hi:[1,0]
	v_rcp_f32_e32 v166, v166
	v_rcp_f32_e32 v167, v167
	v_rcp_f32_e32 v168, v168
	v_rcp_f32_e32 v169, v169
	v_rcp_f32_e32 v170, v170
	v_rcp_f32_e32 v171, v171
	v_rcp_f32_e32 v172, v172
	v_rcp_f32_e32 v173, v173
	v_pk_mul_f32 v[142:143], v[142:143], v[166:167]
	v_pk_mul_f32 v[144:145], v[144:145], v[168:169]
	v_pk_mul_f32 v[138:139], v[138:139], v[170:171]
	v_pk_mul_f32 v[140:141], v[140:141], v[172:173]
	v_fmac_f32_e32 v183, v142, v142
	v_fmac_f32_e32 v183, v143, v143
	v_fmac_f32_e32 v183, v144, v144
	v_fmac_f32_e32 v183, v145, v145
	v_fmac_f32_e32 v183, v138, v138
	v_fmac_f32_e32 v183, v139, v139
	v_fmac_f32_e32 v183, v140, v140
	v_fmac_f32_e32 v183, v141, v141
	v_cvt_pk_bf16_f32 v166, v142, v143
	v_cvt_pk_bf16_f32 v167, v144, v145
	v_cvt_pk_bf16_f32 v168, v138, v139
	v_cvt_pk_bf16_f32 v169, v140, v141
	global_store_dwordx4 v178, v[166:169], s[48:49] offset:0
	s_nop 1
	v_pk_fma_f32 v[134:135], v[134:135], v[242:243], v[38:39] op_sel:[0,1,0]
	v_pk_fma_f32 v[136:137], v[136:137], v[242:243], v[40:41] op_sel:[0,1,0]
	v_pk_fma_f32 v[130:131], v[130:131], v[242:243], v[46:47] op_sel:[0,1,0]
	v_pk_fma_f32 v[132:133], v[132:133], v[242:243], v[48:49] op_sel:[0,1,0]
	v_pk_mul_f32 v[166:167], v[134:135], v[134:135]
	v_pk_mul_f32 v[168:169], v[136:137], v[136:137]
	v_pk_mul_f32 v[170:171], v[130:131], v[130:131]
	v_pk_mul_f32 v[172:173], v[132:133], v[132:133]
	v_pk_fma_f32 v[166:167], v[166:167], s[32:33], 1.0 op_sel_hi:[1,0,0]
	v_pk_fma_f32 v[168:169], v[168:169], s[32:33], 1.0 op_sel_hi:[1,0,0]
	v_pk_fma_f32 v[170:171], v[170:171], s[32:33], 1.0 op_sel_hi:[1,0,0]
	v_pk_fma_f32 v[172:173], v[172:173], s[32:33], 1.0 op_sel_hi:[1,0,0]
	v_pk_mul_f32 v[166:167], v[166:167], v[134:135]
	v_pk_mul_f32 v[168:169], v[168:169], v[136:137]
	v_pk_mul_f32 v[170:171], v[170:171], v[130:131]
	v_pk_mul_f32 v[172:173], v[172:173], v[132:133]
	v_pk_mul_f32 v[166:167], v[166:167], s[100:101] op_sel_hi:[1,0]
	v_pk_mul_f32 v[168:169], v[168:169], s[100:101] op_sel_hi:[1,0]
	v_pk_mul_f32 v[170:171], v[170:171], s[100:101] op_sel_hi:[1,0]
	v_pk_mul_f32 v[172:173], v[172:173], s[100:101] op_sel_hi:[1,0]
	v_exp_f32_e32 v166, v166
	v_exp_f32_e32 v167, v167
	v_exp_f32_e32 v168, v168
	v_exp_f32_e32 v169, v169
	v_exp_f32_e32 v170, v170
	v_exp_f32_e32 v171, v171
	v_exp_f32_e32 v172, v172
	v_exp_f32_e32 v173, v173
	v_pk_add_f32 v[166:167], v[166:167], 1.0 op_sel_hi:[1,0]
; DEV float silu_f(float x) { return x * __builtin_amdgcn_rcpf(1.f + __expf(-x)); }
; DEV float gelu_f(float x) { const float t = 1.5957691216f * (x + 0.044715f * x * x * x); return x * __builtin_amdgcn_rcpf(1.f + __expf(-t)); }
; DEV u32x4 pack8(const float (&f)[8]) { u32x4 w; w.x = cvt_pk_bf16(f[0], f[1]); w.y = cvt_pk_bf16(f[2], f[3]); w.z = cvt_pk_bf16(f[4], f[5]); w.w = cvt_pk_bf16(f[6], f[7]); return w; }
;     DEV void operator()(const f32x4 (&acc)[2][2][4][2], const Unit& u, int wr, int wc, int fr, int fq) const {
;     ...
;         for (int ai = 0; ai < 2; ++ai)
; #pragma unroll
;             for (int m = 0; m < 4; ++m) {
;                 const int row = row0 + ai * 128 + m * 16; float ss = 0.f; const float rstd = rstd8[ai * 4 + m];
; #pragma unroll
;                 for (int bj = 0; bj < 2; ++bj) {
;                     float v[8];
; #pragma unroll
;                     for (int n = 0; n < 2; ++n)
; #pragma unroll
;                         for (int j = 0; j < 4; ++j) { float x = acc[ai][bj][m][n][j] * rstd + sw[bj][n][j]; if (act == 1) x = silu_f(x); else if (act == 2) x = gelu_f(x); v[4 * n + j] = x; ss += x * x; }
;                     *(u32x4*)(Z + (size_t)row * ZW + col0 + bj * 128) = pack8(v);
	v_pk_add_f32 v[168:169], v[168:169], 1.0 op_sel_hi:[1,0]
	v_pk_add_f32 v[170:171], v[170:171], 1.0 op_sel_hi:[1,0]
	v_pk_add_f32 v[172:173], v[172:173], 1.0 op_sel_hi:[1,0]
	v_rcp_f32_e32 v166, v166
	v_rcp_f32_e32 v167, v167
	v_rcp_f32_e32 v168, v168
	v_rcp_f32_e32 v169, v169
	v_rcp_f32_e32 v170, v170
	v_rcp_f32_e32 v171, v171
	v_rcp_f32_e32 v172, v172
	v_rcp_f32_e32 v173, v173
	v_pk_mul_f32 v[134:135], v[134:135], v[166:167]
	v_pk_mul_f32 v[136:137], v[136:137], v[168:169]
	v_pk_mul_f32 v[130:131], v[130:131], v[170:171]
	v_pk_mul_f32 v[132:133], v[132:133], v[172:173]
	v_fmac_f32_e32 v183, v134, v134
	v_fmac_f32_e32 v183, v135, v135
	v_fmac_f32_e32 v183, v136, v136
	v_fmac_f32_e32 v183, v137, v137
	v_fmac_f32_e32 v183, v130, v130
	v_fmac_f32_e32 v183, v131, v131
	v_fmac_f32_e32 v183, v132, v132
	v_fmac_f32_e32 v183, v133, v133
	v_cvt_pk_bf16_f32 v166, v134, v135
	v_cvt_pk_bf16_f32 v167, v136, v137
	v_cvt_pk_bf16_f32 v168, v130, v131
	v_cvt_pk_bf16_f32 v169, v132, v133
	global_store_dwordx4 v178, v[166:169], s[48:49] offset:256
	s_nop 1
	s_add_u32 s46, s48, 0x16000
	s_addc_u32 s47, s49, 0
	v_pk_fma_f32 v[126:127], v[126:127], v[244:245], v[22:23] op_sel_hi:[1,0,1]
	v_pk_fma_f32 v[128:129], v[128:129], v[244:245], v[24:25] op_sel_hi:[1,0,1]
	v_pk_fma_f32 v[122:123], v[122:123], v[244:245], v[30:31] op_sel_hi:[1,0,1]
	v_pk_fma_f32 v[124:125], v[124:125], v[244:245], v[32:33] op_sel_hi:[1,0,1]
	v_pk_mul_f32 v[166:167], v[126:127], v[126:127]
	v_pk_mul_f32 v[168:169], v[128:129], v[128:129]
	v_pk_mul_f32 v[170:171], v[122:123], v[122:123]
	v_pk_mul_f32 v[172:173], v[124:125], v[124:125]
	v_pk_fma_f32 v[166:167], v[166:167], s[32:33], 1.0 op_sel_hi:[1,0,0]
	v_pk_fma_f32 v[168:169], v[168:169], s[32:33], 1.0 op_sel_hi:[1,0,0]
	v_pk_fma_f32 v[170:171], v[170:171], s[32:33], 1.0 op_sel_hi:[1,0,0]
	v_pk_fma_f32 v[172:173], v[172:173], s[32:33], 1.0 op_sel_hi:[1,0,0]
	v_pk_mul_f32 v[166:167], v[166:167], v[126:127]
	v_pk_mul_f32 v[168:169], v[168:169], v[128:129]
	v_pk_mul_f32 v[170:171], v[170:171], v[122:123]
	v_pk_mul_f32 v[172:173], v[172:173], v[124:125]
	v_pk_mul_f32 v[166:167], v[166:167], s[100:101] op_sel_hi:[1,0]
	v_pk_mul_f32 v[168:169], v[168:169], s[100:101] op_sel_hi:[1,0]
	v_pk_mul_f32 v[170:171], v[170:171], s[100:101] op_sel_hi:[1,0]
	v_pk_mul_f32 v[172:173], v[172:173], s[100:101] op_sel_hi:[1,0]
	v_exp_f32_e32 v166, v166
	v_exp_f32_e32 v167, v167
	v_exp_f32_e32 v168, v168
	v_exp_f32_e32 v169, v169
	v_exp_f32_e32 v170, v170
	v_exp_f32_e32 v171, v171
	v_exp_f32_e32 v172, v172
	v_exp_f32_e32 v173, v173
	v_pk_add_f32 v[166:167], v[166:167], 1.0 op_sel_hi:[1,0]
	v_pk_add_f32 v[168:169], v[168:169], 1.0 op_sel_hi:[1,0]
	v_pk_add_f32 v[170:171], v[170:171], 1.0 op_sel_hi:[1,0]
	v_pk_add_f32 v[172:173], v[172:173], 1.0 op_sel_hi:[1,0]
	v_rcp_f32_e32 v166, v166
	v_rcp_f32_e32 v167, v167
	v_rcp_f32_e32 v168, v168
	v_rcp_f32_e32 v169, v169
	v_rcp_f32_e32 v170, v170
	v_rcp_f32_e32 v171, v171
	v_rcp_f32_e32 v172, v172
	v_rcp_f32_e32 v173, v173
	v_pk_mul_f32 v[126:127], v[126:127], v[166:167]
	v_pk_mul_f32 v[128:129], v[128:129], v[168:169]
	v_pk_mul_f32 v[122:123], v[122:123], v[170:171]
	v_pk_mul_f32 v[124:125], v[124:125], v[172:173]
	v_fmac_f32_e32 v184, v126, v126
	v_fmac_f32_e32 v184, v127, v127
	v_fmac_f32_e32 v184, v128, v128
	v_fmac_f32_e32 v184, v129, v129
	v_fmac_f32_e32 v184, v122, v122
	v_fmac_f32_e32 v184, v123, v123
	v_fmac_f32_e32 v184, v124, v124
	v_fmac_f32_e32 v184, v125, v125
	v_cvt_pk_bf16_f32 v166, v126, v127
	v_cvt_pk_bf16_f32 v167, v128, v129
	v_cvt_pk_bf16_f32 v168, v122, v123
	v_cvt_pk_bf16_f32 v169, v124, v125
	global_store_dwordx4 v178, v[166:169], s[46:47] offset:0
	s_nop 1
	v_pk_fma_f32 v[118:119], v[118:119], v[244:245], v[38:39] op_sel_hi:[1,0,1]
	v_pk_fma_f32 v[120:121], v[120:121], v[244:245], v[40:41] op_sel_hi:[1,0,1]
	v_pk_fma_f32 v[114:115], v[114:115], v[244:245], v[46:47] op_sel_hi:[1,0,1]
	v_pk_fma_f32 v[116:117], v[116:117], v[244:245], v[48:49] op_sel_hi:[1,0,1]
	v_pk_mul_f32 v[166:167], v[118:119], v[118:119]
	v_pk_mul_f32 v[168:169], v[120:121], v[120:121]
	v_pk_mul_f32 v[170:171], v[114:115], v[114:115]
	v_pk_mul_f32 v[172:173], v[116:117], v[116:117]
	v_pk_fma_f32 v[166:167], v[166:167], s[32:33], 1.0 op_sel_hi:[1,0,0]
	v_pk_fma_f32 v[168:169], v[168:169], s[32:33], 1.0 op_sel_hi:[1,0,0]
	v_pk_fma_f32 v[170:171], v[170:171], s[32:33], 1.0 op_sel_hi:[1,0,0]
	v_pk_fma_f32 v[172:173], v[172:173], s[32:33], 1.0 op_sel_hi:[1,0,0]
	v_pk_mul_f32 v[166:167], v[166:167], v[118:119]
	v_pk_mul_f32 v[168:169], v[168:169], v[120:121]
	v_pk_mul_f32 v[170:171], v[170:171], v[114:115]
	v_pk_mul_f32 v[172:173], v[172:173], v[116:117]
	v_pk_mul_f32 v[166:167], v[166:167], s[100:101] op_sel_hi:[1,0]
	v_pk_mul_f32 v[168:169], v[168:169], s[100:101] op_sel_hi:[1,0]
	v_pk_mul_f32 v[170:171], v[170:171], s[100:101] op_sel_hi:[1,0]
	v_pk_mul_f32 v[172:173], v[172:173], s[100:101] op_sel_hi:[1,0]
	v_exp_f32_e32 v166, v166
	v_exp_f32_e32 v167, v167
	v_exp_f32_e32 v168, v168
	v_exp_f32_e32 v169, v169
	v_exp_f32_e32 v170, v170
	v_exp_f32_e32 v171, v171
	v_exp_f32_e32 v172, v172
	v_exp_f32_e32 v173, v173
	v_pk_add_f32 v[166:167], v[166:167], 1.0 op_sel_hi:[1,0]
	v_pk_add_f32 v[168:169], v[168:169], 1.0 op_sel_hi:[1,0]
	v_pk_add_f32 v[170:171], v[170:171], 1.0 op_sel_hi:[1,0]
	v_pk_add_f32 v[172:173], v[172:173], 1.0 op_sel_hi:[1,0]
	v_rcp_f32_e32 v166, v166
	v_rcp_f32_e32 v167, v167
	v_rcp_f32_e32 v168, v168
	v_rcp_f32_e32 v169, v169
	v_rcp_f32_e32 v170, v170
	v_rcp_f32_e32 v171, v171
	v_rcp_f32_e32 v172, v172
	v_rcp_f32_e32 v173, v173
	v_pk_mul_f32 v[118:119], v[118:119], v[166:167]
	v_pk_mul_f32 v[120:121], v[120:121], v[168:169]
; DEV float silu_f(float x) { return x * __builtin_amdgcn_rcpf(1.f + __expf(-x)); }
; DEV float gelu_f(float x) { const float t = 1.5957691216f * (x + 0.044715f * x * x * x); return x * __builtin_amdgcn_rcpf(1.f + __expf(-t)); }
; DEV u32x4 pack8(const float (&f)[8]) { u32x4 w; w.x = cvt_pk_bf16(f[0], f[1]); w.y = cvt_pk_bf16(f[2], f[3]); w.z = cvt_pk_bf16(f[4], f[5]); w.w = cvt_pk_bf16(f[6], f[7]); return w; }
;     DEV void operator()(const f32x4 (&acc)[2][2][4][2], const Unit& u, int wr, int wc, int fr, int fq) const {
;     ...
;         for (int ai = 0; ai < 2; ++ai)
; #pragma unroll
;             for (int m = 0; m < 4; ++m) {
;                 const int row = row0 + ai * 128 + m * 16; float ss = 0.f; const float rstd = rstd8[ai * 4 + m];
; #pragma unroll
;                 for (int bj = 0; bj < 2; ++bj) {
;                     float v[8];
; #pragma unroll
;                     for (int n = 0; n < 2; ++n)
; #pragma unroll
;                         for (int j = 0; j < 4; ++j) { float x = acc[ai][bj][m][n][j] * rstd + sw[bj][n][j]; if (act == 1) x = silu_f(x); else if (act == 2) x = gelu_f(x); v[4 * n + j] = x; ss += x * x; }
;                     *(u32x4*)(Z + (size_t)row * ZW + col0 + bj * 128) = pack8(v);
	v_pk_mul_f32 v[114:115], v[114:115], v[170:171]
	v_pk_mul_f32 v[116:117], v[116:117], v[172:173]
	v_fmac_f32_e32 v184, v118, v118
	v_fmac_f32_e32 v184, v119, v119
	v_fmac_f32_e32 v184, v120, v120
	v_fmac_f32_e32 v184, v121, v121
	v_fmac_f32_e32 v184, v114, v114
	v_fmac_f32_e32 v184, v115, v115
	v_fmac_f32_e32 v184, v116, v116
	v_fmac_f32_e32 v184, v117, v117
	v_cvt_pk_bf16_f32 v166, v118, v119
	v_cvt_pk_bf16_f32 v167, v120, v121
	v_cvt_pk_bf16_f32 v168, v114, v115
	v_cvt_pk_bf16_f32 v169, v116, v117
	global_store_dwordx4 v178, v[166:169], s[46:47] offset:256
	s_nop 1
	s_add_u32 s46, s48, 0x2c000
	s_addc_u32 s47, s49, 0
	v_pk_fma_f32 v[110:111], v[110:111], v[244:245], v[22:23] op_sel:[0,1,0]
	v_pk_fma_f32 v[112:113], v[112:113], v[244:245], v[24:25] op_sel:[0,1,0]
	v_pk_fma_f32 v[106:107], v[106:107], v[244:245], v[30:31] op_sel:[0,1,0]
	v_pk_fma_f32 v[108:109], v[108:109], v[244:245], v[32:33] op_sel:[0,1,0]
	v_pk_mul_f32 v[166:167], v[110:111], v[110:111]
	v_pk_mul_f32 v[168:169], v[112:113], v[112:113]
	v_pk_mul_f32 v[170:171], v[106:107], v[106:107]
	v_pk_mul_f32 v[172:173], v[108:109], v[108:109]
	v_pk_fma_f32 v[166:167], v[166:167], s[32:33], 1.0 op_sel_hi:[1,0,0]
	v_pk_fma_f32 v[168:169], v[168:169], s[32:33], 1.0 op_sel_hi:[1,0,0]
	v_pk_fma_f32 v[170:171], v[170:171], s[32:33], 1.0 op_sel_hi:[1,0,0]
	v_pk_fma_f32 v[172:173], v[172:173], s[32:33], 1.0 op_sel_hi:[1,0,0]
	v_pk_mul_f32 v[166:167], v[166:167], v[110:111]
	v_pk_mul_f32 v[168:169], v[168:169], v[112:113]
	v_pk_mul_f32 v[170:171], v[170:171], v[106:107]
	v_pk_mul_f32 v[172:173], v[172:173], v[108:109]
	v_pk_mul_f32 v[166:167], v[166:167], s[100:101] op_sel_hi:[1,0]
	v_pk_mul_f32 v[168:169], v[168:169], s[100:101] op_sel_hi:[1,0]
	v_pk_mul_f32 v[170:171], v[170:171], s[100:101] op_sel_hi:[1,0]
	v_pk_mul_f32 v[172:173], v[172:173], s[100:101] op_sel_hi:[1,0]
	v_exp_f32_e32 v166, v166
	v_exp_f32_e32 v167, v167
	v_exp_f32_e32 v168, v168
	v_exp_f32_e32 v169, v169
	v_exp_f32_e32 v170, v170
	v_exp_f32_e32 v171, v171
	v_exp_f32_e32 v172, v172
	v_exp_f32_e32 v173, v173
	v_pk_add_f32 v[166:167], v[166:167], 1.0 op_sel_hi:[1,0]
	v_pk_add_f32 v[168:169], v[168:169], 1.0 op_sel_hi:[1,0]
	v_pk_add_f32 v[170:171], v[170:171], 1.0 op_sel_hi:[1,0]
	v_pk_add_f32 v[172:173], v[172:173], 1.0 op_sel_hi:[1,0]
	v_rcp_f32_e32 v166, v166
	v_rcp_f32_e32 v167, v167
	v_rcp_f32_e32 v168, v168
	v_rcp_f32_e32 v169, v169
	v_rcp_f32_e32 v170, v170
	v_rcp_f32_e32 v171, v171
	v_rcp_f32_e32 v172, v172
	v_rcp_f32_e32 v173, v173
	v_pk_mul_f32 v[110:111], v[110:111], v[166:167]
	v_pk_mul_f32 v[112:113], v[112:113], v[168:169]
	v_pk_mul_f32 v[106:107], v[106:107], v[170:171]
	v_pk_mul_f32 v[108:109], v[108:109], v[172:173]
	v_fmac_f32_e32 v185, v110, v110
	v_fmac_f32_e32 v185, v111, v111
	v_fmac_f32_e32 v185, v112, v112
	v_fmac_f32_e32 v185, v113, v113
	v_fmac_f32_e32 v185, v106, v106
	v_fmac_f32_e32 v185, v107, v107
	v_fmac_f32_e32 v185, v108, v108
	v_fmac_f32_e32 v185, v109, v109
	v_cvt_pk_bf16_f32 v166, v110, v111
	v_cvt_pk_bf16_f32 v167, v112, v113
	v_cvt_pk_bf16_f32 v168, v106, v107
	v_cvt_pk_bf16_f32 v169, v108, v109
	global_store_dwordx4 v178, v[166:169], s[46:47] offset:0
	s_nop 1
	v_pk_fma_f32 v[102:103], v[102:103], v[244:245], v[38:39] op_sel:[0,1,0]
	v_pk_fma_f32 v[104:105], v[104:105], v[244:245], v[40:41] op_sel:[0,1,0]
	v_pk_fma_f32 v[98:99], v[98:99], v[244:245], v[46:47] op_sel:[0,1,0]
	v_pk_fma_f32 v[100:101], v[100:101], v[244:245], v[48:49] op_sel:[0,1,0]
	v_pk_mul_f32 v[166:167], v[102:103], v[102:103]
	v_pk_mul_f32 v[168:169], v[104:105], v[104:105]
	v_pk_mul_f32 v[170:171], v[98:99], v[98:99]
	v_pk_mul_f32 v[172:173], v[100:101], v[100:101]
	v_pk_fma_f32 v[166:167], v[166:167], s[32:33], 1.0 op_sel_hi:[1,0,0]
	v_pk_fma_f32 v[168:169], v[168:169], s[32:33], 1.0 op_sel_hi:[1,0,0]
	v_pk_fma_f32 v[170:171], v[170:171], s[32:33], 1.0 op_sel_hi:[1,0,0]
	v_pk_fma_f32 v[172:173], v[172:173], s[32:33], 1.0 op_sel_hi:[1,0,0]
	v_pk_mul_f32 v[166:167], v[166:167], v[102:103]
	v_pk_mul_f32 v[168:169], v[168:169], v[104:105]
	v_pk_mul_f32 v[170:171], v[170:171], v[98:99]
	v_pk_mul_f32 v[172:173], v[172:173], v[100:101]
	v_pk_mul_f32 v[166:167], v[166:167], s[100:101] op_sel_hi:[1,0]
	v_pk_mul_f32 v[168:169], v[168:169], s[100:101] op_sel_hi:[1,0]
	v_pk_mul_f32 v[170:171], v[170:171], s[100:101] op_sel_hi:[1,0]
	v_pk_mul_f32 v[172:173], v[172:173], s[100:101] op_sel_hi:[1,0]
	v_exp_f32_e32 v166, v166
	v_exp_f32_e32 v167, v167
	v_exp_f32_e32 v168, v168
	v_exp_f32_e32 v169, v169
	v_exp_f32_e32 v170, v170
	v_exp_f32_e32 v171, v171
	v_exp_f32_e32 v172, v172
	v_exp_f32_e32 v173, v173
	v_pk_add_f32 v[166:167], v[166:167], 1.0 op_sel_hi:[1,0]
	v_pk_add_f32 v[168:169], v[168:169], 1.0 op_sel_hi:[1,0]
	v_pk_add_f32 v[170:171], v[170:171], 1.0 op_sel_hi:[1,0]
	v_pk_add_f32 v[172:173], v[172:173], 1.0 op_sel_hi:[1,0]
	v_rcp_f32_e32 v166, v166
	v_rcp_f32_e32 v167, v167
	v_rcp_f32_e32 v168, v168
	v_rcp_f32_e32 v169, v169
	v_rcp_f32_e32 v170, v170
	v_rcp_f32_e32 v171, v171
	v_rcp_f32_e32 v172, v172
	v_rcp_f32_e32 v173, v173
	v_pk_mul_f32 v[102:103], v[102:103], v[166:167]
	v_pk_mul_f32 v[104:105], v[104:105], v[168:169]
	v_pk_mul_f32 v[98:99], v[98:99], v[170:171]
	v_pk_mul_f32 v[100:101], v[100:101], v[172:173]
	v_fmac_f32_e32 v185, v102, v102
	v_fmac_f32_e32 v185, v103, v103
	v_fmac_f32_e32 v185, v104, v104
	v_fmac_f32_e32 v185, v105, v105
	v_fmac_f32_e32 v185, v98, v98
	v_fmac_f32_e32 v185, v99, v99
	v_fmac_f32_e32 v185, v100, v100
	v_fmac_f32_e32 v185, v101, v101
	v_cvt_pk_bf16_f32 v166, v102, v103
	v_cvt_pk_bf16_f32 v167, v104, v105
	v_cvt_pk_bf16_f32 v168, v98, v99
	v_cvt_pk_bf16_f32 v169, v100, v101
; DEV float silu_f(float x) { return x * __builtin_amdgcn_rcpf(1.f + __expf(-x)); }
; DEV float gelu_f(float x) { const float t = 1.5957691216f * (x + 0.044715f * x * x * x); return x * __builtin_amdgcn_rcpf(1.f + __expf(-t)); }
; DEV u32x4 pack8(const float (&f)[8]) { u32x4 w; w.x = cvt_pk_bf16(f[0], f[1]); w.y = cvt_pk_bf16(f[2], f[3]); w.z = cvt_pk_bf16(f[4], f[5]); w.w = cvt_pk_bf16(f[6], f[7]); return w; }
;     DEV void operator()(const f32x4 (&acc)[2][2][4][2], const Unit& u, int wr, int wc, int fr, int fq) const {
;     ...
;         for (int ai = 0; ai < 2; ++ai)
; #pragma unroll
;             for (int m = 0; m < 4; ++m) {
;                 const int row = row0 + ai * 128 + m * 16; float ss = 0.f; const float rstd = rstd8[ai * 4 + m];
; #pragma unroll
;                 for (int bj = 0; bj < 2; ++bj) {
;                     float v[8];
; #pragma unroll
;                     for (int n = 0; n < 2; ++n)
; #pragma unroll
;                         for (int j = 0; j < 4; ++j) { float x = acc[ai][bj][m][n][j] * rstd + sw[bj][n][j]; if (act == 1) x = silu_f(x); else if (act == 2) x = gelu_f(x); v[4 * n + j] = x; ss += x * x; }
;                     *(u32x4*)(Z + (size_t)row * ZW + col0 + bj * 128) = pack8(v);
	global_store_dwordx4 v178, v[166:169], s[46:47] offset:256
	s_nop 1
	s_add_u32 s46, s48, 0x42000
	s_addc_u32 s47, s49, 0
	v_pk_fma_f32 v[94:95], v[94:95], v[246:247], v[22:23] op_sel_hi:[1,0,1]
	v_pk_fma_f32 v[96:97], v[96:97], v[246:247], v[24:25] op_sel_hi:[1,0,1]
	v_pk_fma_f32 v[90:91], v[90:91], v[246:247], v[30:31] op_sel_hi:[1,0,1]
	v_pk_fma_f32 v[92:93], v[92:93], v[246:247], v[32:33] op_sel_hi:[1,0,1]
	v_pk_mul_f32 v[166:167], v[94:95], v[94:95]
	v_pk_mul_f32 v[168:169], v[96:97], v[96:97]
	v_pk_mul_f32 v[170:171], v[90:91], v[90:91]
	v_pk_mul_f32 v[172:173], v[92:93], v[92:93]
	v_pk_fma_f32 v[166:167], v[166:167], s[32:33], 1.0 op_sel_hi:[1,0,0]
	v_pk_fma_f32 v[168:169], v[168:169], s[32:33], 1.0 op_sel_hi:[1,0,0]
	v_pk_fma_f32 v[170:171], v[170:171], s[32:33], 1.0 op_sel_hi:[1,0,0]
	v_pk_fma_f32 v[172:173], v[172:173], s[32:33], 1.0 op_sel_hi:[1,0,0]
	v_pk_mul_f32 v[166:167], v[166:167], v[94:95]
	v_pk_mul_f32 v[168:169], v[168:169], v[96:97]
	v_pk_mul_f32 v[170:171], v[170:171], v[90:91]
	v_pk_mul_f32 v[172:173], v[172:173], v[92:93]
	v_pk_mul_f32 v[166:167], v[166:167], s[100:101] op_sel_hi:[1,0]
	v_pk_mul_f32 v[168:169], v[168:169], s[100:101] op_sel_hi:[1,0]
	v_pk_mul_f32 v[170:171], v[170:171], s[100:101] op_sel_hi:[1,0]
	v_pk_mul_f32 v[172:173], v[172:173], s[100:101] op_sel_hi:[1,0]
	v_exp_f32_e32 v166, v166
	v_exp_f32_e32 v167, v167
	v_exp_f32_e32 v168, v168
	v_exp_f32_e32 v169, v169
	v_exp_f32_e32 v170, v170
	v_exp_f32_e32 v171, v171
	v_exp_f32_e32 v172, v172
	v_exp_f32_e32 v173, v173
	v_pk_add_f32 v[166:167], v[166:167], 1.0 op_sel_hi:[1,0]
	v_pk_add_f32 v[168:169], v[168:169], 1.0 op_sel_hi:[1,0]
	v_pk_add_f32 v[170:171], v[170:171], 1.0 op_sel_hi:[1,0]
	v_pk_add_f32 v[172:173], v[172:173], 1.0 op_sel_hi:[1,0]
	v_rcp_f32_e32 v166, v166
	v_rcp_f32_e32 v167, v167
	v_rcp_f32_e32 v168, v168
	v_rcp_f32_e32 v169, v169
	v_rcp_f32_e32 v170, v170
	v_rcp_f32_e32 v171, v171
	v_rcp_f32_e32 v172, v172
	v_rcp_f32_e32 v173, v173
	v_pk_mul_f32 v[94:95], v[94:95], v[166:167]
	v_pk_mul_f32 v[96:97], v[96:97], v[168:169]
	v_pk_mul_f32 v[90:91], v[90:91], v[170:171]
	v_pk_mul_f32 v[92:93], v[92:93], v[172:173]
	v_fmac_f32_e32 v186, v94, v94
	v_fmac_f32_e32 v186, v95, v95
	v_fmac_f32_e32 v186, v96, v96
	v_fmac_f32_e32 v186, v97, v97
	v_fmac_f32_e32 v186, v90, v90
	v_fmac_f32_e32 v186, v91, v91
	v_fmac_f32_e32 v186, v92, v92
	v_fmac_f32_e32 v186, v93, v93
	v_cvt_pk_bf16_f32 v166, v94, v95
	v_cvt_pk_bf16_f32 v167, v96, v97
	v_cvt_pk_bf16_f32 v168, v90, v91
	v_cvt_pk_bf16_f32 v169, v92, v93
	global_store_dwordx4 v178, v[166:169], s[46:47] offset:0
	s_nop 1
	v_pk_fma_f32 v[86:87], v[86:87], v[246:247], v[38:39] op_sel_hi:[1,0,1]
	v_pk_fma_f32 v[88:89], v[88:89], v[246:247], v[40:41] op_sel_hi:[1,0,1]
	v_pk_fma_f32 v[82:83], v[82:83], v[246:247], v[46:47] op_sel_hi:[1,0,1]
	v_pk_fma_f32 v[84:85], v[84:85], v[246:247], v[48:49] op_sel_hi:[1,0,1]
	v_pk_mul_f32 v[166:167], v[86:87], v[86:87]
	v_pk_mul_f32 v[168:169], v[88:89], v[88:89]
	v_pk_mul_f32 v[170:171], v[82:83], v[82:83]
	v_pk_mul_f32 v[172:173], v[84:85], v[84:85]
	v_pk_fma_f32 v[166:167], v[166:167], s[32:33], 1.0 op_sel_hi:[1,0,0]
	v_pk_fma_f32 v[168:169], v[168:169], s[32:33], 1.0 op_sel_hi:[1,0,0]
	v_pk_fma_f32 v[170:171], v[170:171], s[32:33], 1.0 op_sel_hi:[1,0,0]
	v_pk_fma_f32 v[172:173], v[172:173], s[32:33], 1.0 op_sel_hi:[1,0,0]
	v_pk_mul_f32 v[166:167], v[166:167], v[86:87]
	v_pk_mul_f32 v[168:169], v[168:169], v[88:89]
	v_pk_mul_f32 v[170:171], v[170:171], v[82:83]
	v_pk_mul_f32 v[172:173], v[172:173], v[84:85]
	v_pk_mul_f32 v[166:167], v[166:167], s[100:101] op_sel_hi:[1,0]
	v_pk_mul_f32 v[168:169], v[168:169], s[100:101] op_sel_hi:[1,0]
	v_pk_mul_f32 v[170:171], v[170:171], s[100:101] op_sel_hi:[1,0]
	v_pk_mul_f32 v[172:173], v[172:173], s[100:101] op_sel_hi:[1,0]
	v_exp_f32_e32 v166, v166
	v_exp_f32_e32 v167, v167
	v_exp_f32_e32 v168, v168
	v_exp_f32_e32 v169, v169
	v_exp_f32_e32 v170, v170
	v_exp_f32_e32 v171, v171
	v_exp_f32_e32 v172, v172
	v_exp_f32_e32 v173, v173
	v_pk_add_f32 v[166:167], v[166:167], 1.0 op_sel_hi:[1,0]
	v_pk_add_f32 v[168:169], v[168:169], 1.0 op_sel_hi:[1,0]
	v_pk_add_f32 v[170:171], v[170:171], 1.0 op_sel_hi:[1,0]
	v_pk_add_f32 v[172:173], v[172:173], 1.0 op_sel_hi:[1,0]
	v_rcp_f32_e32 v166, v166
	v_rcp_f32_e32 v167, v167
	v_rcp_f32_e32 v168, v168
	v_rcp_f32_e32 v169, v169
	v_rcp_f32_e32 v170, v170
	v_rcp_f32_e32 v171, v171
	v_rcp_f32_e32 v172, v172
	v_rcp_f32_e32 v173, v173
	v_pk_mul_f32 v[86:87], v[86:87], v[166:167]
	v_pk_mul_f32 v[88:89], v[88:89], v[168:169]
	v_pk_mul_f32 v[82:83], v[82:83], v[170:171]
	v_pk_mul_f32 v[84:85], v[84:85], v[172:173]
	v_fmac_f32_e32 v186, v86, v86
	v_fmac_f32_e32 v186, v87, v87
	v_fmac_f32_e32 v186, v88, v88
	v_fmac_f32_e32 v186, v89, v89
	v_fmac_f32_e32 v186, v82, v82
	v_fmac_f32_e32 v186, v83, v83
	v_fmac_f32_e32 v186, v84, v84
	v_fmac_f32_e32 v186, v85, v85
	v_cvt_pk_bf16_f32 v166, v86, v87
	v_cvt_pk_bf16_f32 v167, v88, v89
	v_cvt_pk_bf16_f32 v168, v82, v83
	v_cvt_pk_bf16_f32 v169, v84, v85
	global_store_dwordx4 v178, v[166:169], s[46:47] offset:256
	s_nop 1
	s_add_u32 s46, s48, 0xb0000
	s_addc_u32 s47, s49, 0
	v_pk_fma_f32 v[78:79], v[78:79], v[246:247], v[22:23] op_sel:[0,1,0]
	v_pk_fma_f32 v[80:81], v[80:81], v[246:247], v[24:25] op_sel:[0,1,0]
	v_pk_fma_f32 v[74:75], v[74:75], v[246:247], v[30:31] op_sel:[0,1,0]
	v_pk_fma_f32 v[76:77], v[76:77], v[246:247], v[32:33] op_sel:[0,1,0]
	v_pk_mul_f32 v[166:167], v[78:79], v[78:79]
	v_pk_mul_f32 v[168:169], v[80:81], v[80:81]
	v_pk_mul_f32 v[170:171], v[74:75], v[74:75]
	v_pk_mul_f32 v[172:173], v[76:77], v[76:77]
	v_pk_fma_f32 v[166:167], v[166:167], s[32:33], 1.0 op_sel_hi:[1,0,0]
; DEV float silu_f(float x) { return x * __builtin_amdgcn_rcpf(1.f + __expf(-x)); }
; DEV float gelu_f(float x) { const float t = 1.5957691216f * (x + 0.044715f * x * x * x); return x * __builtin_amdgcn_rcpf(1.f + __expf(-t)); }
; DEV u32x4 pack8(const float (&f)[8]) { u32x4 w; w.x = cvt_pk_bf16(f[0], f[1]); w.y = cvt_pk_bf16(f[2], f[3]); w.z = cvt_pk_bf16(f[4], f[5]); w.w = cvt_pk_bf16(f[6], f[7]); return w; }
;     DEV void operator()(const f32x4 (&acc)[2][2][4][2], const Unit& u, int wr, int wc, int fr, int fq) const {
;     ...
;         for (int ai = 0; ai < 2; ++ai)
; #pragma unroll
;             for (int m = 0; m < 4; ++m) {
;                 const int row = row0 + ai * 128 + m * 16; float ss = 0.f; const float rstd = rstd8[ai * 4 + m];
; #pragma unroll
;                 for (int bj = 0; bj < 2; ++bj) {
;                     float v[8];
; #pragma unroll
;                     for (int n = 0; n < 2; ++n)
; #pragma unroll
;                         for (int j = 0; j < 4; ++j) { float x = acc[ai][bj][m][n][j] * rstd + sw[bj][n][j]; if (act == 1) x = silu_f(x); else if (act == 2) x = gelu_f(x); v[4 * n + j] = x; ss += x * x; }
;                     *(u32x4*)(Z + (size_t)row * ZW + col0 + bj * 128) = pack8(v);
	v_pk_fma_f32 v[168:169], v[168:169], s[32:33], 1.0 op_sel_hi:[1,0,0]
	v_pk_fma_f32 v[170:171], v[170:171], s[32:33], 1.0 op_sel_hi:[1,0,0]
	v_pk_fma_f32 v[172:173], v[172:173], s[32:33], 1.0 op_sel_hi:[1,0,0]
	v_pk_mul_f32 v[166:167], v[166:167], v[78:79]
	v_pk_mul_f32 v[168:169], v[168:169], v[80:81]
	v_pk_mul_f32 v[170:171], v[170:171], v[74:75]
	v_pk_mul_f32 v[172:173], v[172:173], v[76:77]
	v_pk_mul_f32 v[166:167], v[166:167], s[100:101] op_sel_hi:[1,0]
	v_pk_mul_f32 v[168:169], v[168:169], s[100:101] op_sel_hi:[1,0]
	v_pk_mul_f32 v[170:171], v[170:171], s[100:101] op_sel_hi:[1,0]
	v_pk_mul_f32 v[172:173], v[172:173], s[100:101] op_sel_hi:[1,0]
	v_exp_f32_e32 v166, v166
	v_exp_f32_e32 v167, v167
	v_exp_f32_e32 v168, v168
	v_exp_f32_e32 v169, v169
	v_exp_f32_e32 v170, v170
	v_exp_f32_e32 v171, v171
	v_exp_f32_e32 v172, v172
	v_exp_f32_e32 v173, v173
	v_pk_add_f32 v[166:167], v[166:167], 1.0 op_sel_hi:[1,0]
	v_pk_add_f32 v[168:169], v[168:169], 1.0 op_sel_hi:[1,0]
	v_pk_add_f32 v[170:171], v[170:171], 1.0 op_sel_hi:[1,0]
	v_pk_add_f32 v[172:173], v[172:173], 1.0 op_sel_hi:[1,0]
	v_rcp_f32_e32 v166, v166
	v_rcp_f32_e32 v167, v167
	v_rcp_f32_e32 v168, v168
	v_rcp_f32_e32 v169, v169
	v_rcp_f32_e32 v170, v170
	v_rcp_f32_e32 v171, v171
	v_rcp_f32_e32 v172, v172
	v_rcp_f32_e32 v173, v173
	v_pk_mul_f32 v[78:79], v[78:79], v[166:167]
	v_pk_mul_f32 v[80:81], v[80:81], v[168:169]
	v_pk_mul_f32 v[74:75], v[74:75], v[170:171]
	v_pk_mul_f32 v[76:77], v[76:77], v[172:173]
	v_fmac_f32_e32 v187, v78, v78
	v_fmac_f32_e32 v187, v79, v79
	v_fmac_f32_e32 v187, v80, v80
	v_fmac_f32_e32 v187, v81, v81
	v_fmac_f32_e32 v187, v74, v74
	v_fmac_f32_e32 v187, v75, v75
	v_fmac_f32_e32 v187, v76, v76
	v_fmac_f32_e32 v187, v77, v77
	v_cvt_pk_bf16_f32 v166, v78, v79
	v_cvt_pk_bf16_f32 v167, v80, v81
	v_cvt_pk_bf16_f32 v168, v74, v75
	v_cvt_pk_bf16_f32 v169, v76, v77
	global_store_dwordx4 v178, v[166:169], s[46:47] offset:0
	s_nop 1
	v_pk_fma_f32 v[70:71], v[70:71], v[246:247], v[38:39] op_sel:[0,1,0]
	v_pk_fma_f32 v[72:73], v[72:73], v[246:247], v[40:41] op_sel:[0,1,0]
	v_pk_fma_f32 v[66:67], v[66:67], v[246:247], v[46:47] op_sel:[0,1,0]
	v_pk_fma_f32 v[68:69], v[68:69], v[246:247], v[48:49] op_sel:[0,1,0]
	v_pk_mul_f32 v[166:167], v[70:71], v[70:71]
	v_pk_mul_f32 v[168:169], v[72:73], v[72:73]
	v_pk_mul_f32 v[170:171], v[66:67], v[66:67]
	v_pk_mul_f32 v[172:173], v[68:69], v[68:69]
	v_pk_fma_f32 v[166:167], v[166:167], s[32:33], 1.0 op_sel_hi:[1,0,0]
	v_pk_fma_f32 v[168:169], v[168:169], s[32:33], 1.0 op_sel_hi:[1,0,0]
	v_pk_fma_f32 v[170:171], v[170:171], s[32:33], 1.0 op_sel_hi:[1,0,0]
	v_pk_fma_f32 v[172:173], v[172:173], s[32:33], 1.0 op_sel_hi:[1,0,0]
	v_pk_mul_f32 v[166:167], v[166:167], v[70:71]
	v_pk_mul_f32 v[168:169], v[168:169], v[72:73]
	v_pk_mul_f32 v[170:171], v[170:171], v[66:67]
	v_pk_mul_f32 v[172:173], v[172:173], v[68:69]
	v_pk_mul_f32 v[166:167], v[166:167], s[100:101] op_sel_hi:[1,0]
	v_pk_mul_f32 v[168:169], v[168:169], s[100:101] op_sel_hi:[1,0]
	v_pk_mul_f32 v[170:171], v[170:171], s[100:101] op_sel_hi:[1,0]
	v_pk_mul_f32 v[172:173], v[172:173], s[100:101] op_sel_hi:[1,0]
	v_exp_f32_e32 v166, v166
	v_exp_f32_e32 v167, v167
	v_exp_f32_e32 v168, v168
	v_exp_f32_e32 v169, v169
	v_exp_f32_e32 v170, v170
	v_exp_f32_e32 v171, v171
	v_exp_f32_e32 v172, v172
	v_exp_f32_e32 v173, v173
	v_pk_add_f32 v[166:167], v[166:167], 1.0 op_sel_hi:[1,0]
	v_pk_add_f32 v[168:169], v[168:169], 1.0 op_sel_hi:[1,0]
	v_pk_add_f32 v[170:171], v[170:171], 1.0 op_sel_hi:[1,0]
	v_pk_add_f32 v[172:173], v[172:173], 1.0 op_sel_hi:[1,0]
	v_rcp_f32_e32 v166, v166
	v_rcp_f32_e32 v167, v167
	v_rcp_f32_e32 v168, v168
	v_rcp_f32_e32 v169, v169
	v_rcp_f32_e32 v170, v170
	v_rcp_f32_e32 v171, v171
	v_rcp_f32_e32 v172, v172
	v_rcp_f32_e32 v173, v173
	v_pk_mul_f32 v[70:71], v[70:71], v[166:167]
	v_pk_mul_f32 v[72:73], v[72:73], v[168:169]
	v_pk_mul_f32 v[66:67], v[66:67], v[170:171]
	v_pk_mul_f32 v[68:69], v[68:69], v[172:173]
	v_fmac_f32_e32 v187, v70, v70
	v_fmac_f32_e32 v187, v71, v71
	v_fmac_f32_e32 v187, v72, v72
	v_fmac_f32_e32 v187, v73, v73
	v_fmac_f32_e32 v187, v66, v66
	v_fmac_f32_e32 v187, v67, v67
	v_fmac_f32_e32 v187, v68, v68
	v_fmac_f32_e32 v187, v69, v69
	v_cvt_pk_bf16_f32 v166, v70, v71
	v_cvt_pk_bf16_f32 v167, v72, v73
	v_cvt_pk_bf16_f32 v168, v66, v67
	v_cvt_pk_bf16_f32 v169, v68, v69
	global_store_dwordx4 v178, v[166:169], s[46:47] offset:256
	s_nop 1
	s_add_u32 s46, s48, 0xc6000
	s_addc_u32 s47, s49, 0
	v_pk_fma_f32 v[62:63], v[62:63], v[248:249], v[22:23] op_sel_hi:[1,0,1]
	v_pk_fma_f32 v[64:65], v[64:65], v[248:249], v[24:25] op_sel_hi:[1,0,1]
	v_pk_fma_f32 v[58:59], v[58:59], v[248:249], v[30:31] op_sel_hi:[1,0,1]
	v_pk_fma_f32 v[60:61], v[60:61], v[248:249], v[32:33] op_sel_hi:[1,0,1]
	v_pk_mul_f32 v[166:167], v[62:63], v[62:63]
	v_pk_mul_f32 v[168:169], v[64:65], v[64:65]
	v_pk_mul_f32 v[170:171], v[58:59], v[58:59]
	v_pk_mul_f32 v[172:173], v[60:61], v[60:61]
	v_pk_fma_f32 v[166:167], v[166:167], s[32:33], 1.0 op_sel_hi:[1,0,0]
	v_pk_fma_f32 v[168:169], v[168:169], s[32:33], 1.0 op_sel_hi:[1,0,0]
	v_pk_fma_f32 v[170:171], v[170:171], s[32:33], 1.0 op_sel_hi:[1,0,0]
	v_pk_fma_f32 v[172:173], v[172:173], s[32:33], 1.0 op_sel_hi:[1,0,0]
	v_pk_mul_f32 v[166:167], v[166:167], v[62:63]
	v_pk_mul_f32 v[168:169], v[168:169], v[64:65]
	v_pk_mul_f32 v[170:171], v[170:171], v[58:59]
	v_pk_mul_f32 v[172:173], v[172:173], v[60:61]
	v_pk_mul_f32 v[166:167], v[166:167], s[100:101] op_sel_hi:[1,0]
	v_pk_mul_f32 v[168:169], v[168:169], s[100:101] op_sel_hi:[1,0]
	v_pk_mul_f32 v[170:171], v[170:171], s[100:101] op_sel_hi:[1,0]
	v_pk_mul_f32 v[172:173], v[172:173], s[100:101] op_sel_hi:[1,0]
; DEV float silu_f(float x) { return x * __builtin_amdgcn_rcpf(1.f + __expf(-x)); }
; DEV float gelu_f(float x) { const float t = 1.5957691216f * (x + 0.044715f * x * x * x); return x * __builtin_amdgcn_rcpf(1.f + __expf(-t)); }
; DEV u32x4 pack8(const float (&f)[8]) { u32x4 w; w.x = cvt_pk_bf16(f[0], f[1]); w.y = cvt_pk_bf16(f[2], f[3]); w.z = cvt_pk_bf16(f[4], f[5]); w.w = cvt_pk_bf16(f[6], f[7]); return w; }
;     DEV void operator()(const f32x4 (&acc)[2][2][4][2], const Unit& u, int wr, int wc, int fr, int fq) const {
;     ...
;         for (int ai = 0; ai < 2; ++ai)
; #pragma unroll
;             for (int m = 0; m < 4; ++m) {
;                 const int row = row0 + ai * 128 + m * 16; float ss = 0.f; const float rstd = rstd8[ai * 4 + m];
; #pragma unroll
;                 for (int bj = 0; bj < 2; ++bj) {
;                     float v[8];
; #pragma unroll
;                     for (int n = 0; n < 2; ++n)
; #pragma unroll
;                         for (int j = 0; j < 4; ++j) { float x = acc[ai][bj][m][n][j] * rstd + sw[bj][n][j]; if (act == 1) x = silu_f(x); else if (act == 2) x = gelu_f(x); v[4 * n + j] = x; ss += x * x; }
;                     *(u32x4*)(Z + (size_t)row * ZW + col0 + bj * 128) = pack8(v);
	v_exp_f32_e32 v166, v166
	v_exp_f32_e32 v167, v167
	v_exp_f32_e32 v168, v168
	v_exp_f32_e32 v169, v169
	v_exp_f32_e32 v170, v170
	v_exp_f32_e32 v171, v171
	v_exp_f32_e32 v172, v172
	v_exp_f32_e32 v173, v173
	v_pk_add_f32 v[166:167], v[166:167], 1.0 op_sel_hi:[1,0]
	v_pk_add_f32 v[168:169], v[168:169], 1.0 op_sel_hi:[1,0]
	v_pk_add_f32 v[170:171], v[170:171], 1.0 op_sel_hi:[1,0]
	v_pk_add_f32 v[172:173], v[172:173], 1.0 op_sel_hi:[1,0]
	v_rcp_f32_e32 v166, v166
	v_rcp_f32_e32 v167, v167
	v_rcp_f32_e32 v168, v168
	v_rcp_f32_e32 v169, v169
	v_rcp_f32_e32 v170, v170
	v_rcp_f32_e32 v171, v171
	v_rcp_f32_e32 v172, v172
	v_rcp_f32_e32 v173, v173
	v_pk_mul_f32 v[62:63], v[62:63], v[166:167]
	v_pk_mul_f32 v[64:65], v[64:65], v[168:169]
	v_pk_mul_f32 v[58:59], v[58:59], v[170:171]
	v_pk_mul_f32 v[60:61], v[60:61], v[172:173]
	v_fmac_f32_e32 v188, v62, v62
	v_fmac_f32_e32 v188, v63, v63
	v_fmac_f32_e32 v188, v64, v64
	v_fmac_f32_e32 v188, v65, v65
	v_fmac_f32_e32 v188, v58, v58
	v_fmac_f32_e32 v188, v59, v59
	v_fmac_f32_e32 v188, v60, v60
	v_fmac_f32_e32 v188, v61, v61
	v_cvt_pk_bf16_f32 v166, v62, v63
	v_cvt_pk_bf16_f32 v167, v64, v65
	v_cvt_pk_bf16_f32 v168, v58, v59
	v_cvt_pk_bf16_f32 v169, v60, v61
	global_store_dwordx4 v178, v[166:169], s[46:47] offset:0
	s_nop 1
	v_pk_fma_f32 v[54:55], v[54:55], v[248:249], v[38:39] op_sel_hi:[1,0,1]
	v_pk_fma_f32 v[56:57], v[56:57], v[248:249], v[40:41] op_sel_hi:[1,0,1]
	v_pk_fma_f32 v[50:51], v[50:51], v[248:249], v[46:47] op_sel_hi:[1,0,1]
	v_pk_fma_f32 v[52:53], v[52:53], v[248:249], v[48:49] op_sel_hi:[1,0,1]
	v_pk_mul_f32 v[166:167], v[54:55], v[54:55]
	v_pk_mul_f32 v[168:169], v[56:57], v[56:57]
	v_pk_mul_f32 v[170:171], v[50:51], v[50:51]
	v_pk_mul_f32 v[172:173], v[52:53], v[52:53]
	v_pk_fma_f32 v[166:167], v[166:167], s[32:33], 1.0 op_sel_hi:[1,0,0]
	v_pk_fma_f32 v[168:169], v[168:169], s[32:33], 1.0 op_sel_hi:[1,0,0]
	v_pk_fma_f32 v[170:171], v[170:171], s[32:33], 1.0 op_sel_hi:[1,0,0]
	v_pk_fma_f32 v[172:173], v[172:173], s[32:33], 1.0 op_sel_hi:[1,0,0]
	v_pk_mul_f32 v[166:167], v[166:167], v[54:55]
	v_pk_mul_f32 v[168:169], v[168:169], v[56:57]
	v_pk_mul_f32 v[170:171], v[170:171], v[50:51]
	v_pk_mul_f32 v[172:173], v[172:173], v[52:53]
	v_pk_mul_f32 v[166:167], v[166:167], s[100:101] op_sel_hi:[1,0]
	v_pk_mul_f32 v[168:169], v[168:169], s[100:101] op_sel_hi:[1,0]
	v_pk_mul_f32 v[170:171], v[170:171], s[100:101] op_sel_hi:[1,0]
	v_pk_mul_f32 v[172:173], v[172:173], s[100:101] op_sel_hi:[1,0]
	v_exp_f32_e32 v166, v166
	v_exp_f32_e32 v167, v167
	v_exp_f32_e32 v168, v168
	v_exp_f32_e32 v169, v169
	v_exp_f32_e32 v170, v170
	v_exp_f32_e32 v171, v171
	v_exp_f32_e32 v172, v172
	v_exp_f32_e32 v173, v173
	v_pk_add_f32 v[166:167], v[166:167], 1.0 op_sel_hi:[1,0]
	v_pk_add_f32 v[168:169], v[168:169], 1.0 op_sel_hi:[1,0]
	v_pk_add_f32 v[170:171], v[170:171], 1.0 op_sel_hi:[1,0]
	v_pk_add_f32 v[172:173], v[172:173], 1.0 op_sel_hi:[1,0]
	v_rcp_f32_e32 v166, v166
	v_rcp_f32_e32 v167, v167
	v_rcp_f32_e32 v168, v168
	v_rcp_f32_e32 v169, v169
	v_rcp_f32_e32 v170, v170
	v_rcp_f32_e32 v171, v171
	v_rcp_f32_e32 v172, v172
	v_rcp_f32_e32 v173, v173
	v_pk_mul_f32 v[54:55], v[54:55], v[166:167]
	v_pk_mul_f32 v[56:57], v[56:57], v[168:169]
	v_pk_mul_f32 v[50:51], v[50:51], v[170:171]
	v_pk_mul_f32 v[52:53], v[52:53], v[172:173]
	v_fmac_f32_e32 v188, v54, v54
	v_fmac_f32_e32 v188, v55, v55
	v_fmac_f32_e32 v188, v56, v56
	v_fmac_f32_e32 v188, v57, v57
	v_fmac_f32_e32 v188, v50, v50
	v_fmac_f32_e32 v188, v51, v51
	v_fmac_f32_e32 v188, v52, v52
	v_fmac_f32_e32 v188, v53, v53
	v_cvt_pk_bf16_f32 v166, v54, v55
	v_cvt_pk_bf16_f32 v167, v56, v57
	v_cvt_pk_bf16_f32 v168, v50, v51
	v_cvt_pk_bf16_f32 v169, v52, v53
	global_store_dwordx4 v178, v[166:169], s[46:47] offset:256
	s_nop 1
	s_add_u32 s46, s48, 0xdc000
	s_addc_u32 s47, s49, 0
	v_pk_fma_f32 v[42:43], v[42:43], v[248:249], v[22:23] op_sel:[0,1,0]
	v_pk_fma_f32 v[44:45], v[44:45], v[248:249], v[24:25] op_sel:[0,1,0]
	v_pk_fma_f32 v[34:35], v[34:35], v[248:249], v[30:31] op_sel:[0,1,0]
	v_pk_fma_f32 v[36:37], v[36:37], v[248:249], v[32:33] op_sel:[0,1,0]
	v_pk_mul_f32 v[166:167], v[42:43], v[42:43]
	v_pk_mul_f32 v[168:169], v[44:45], v[44:45]
	v_pk_mul_f32 v[170:171], v[34:35], v[34:35]
	v_pk_mul_f32 v[172:173], v[36:37], v[36:37]
	v_pk_fma_f32 v[166:167], v[166:167], s[32:33], 1.0 op_sel_hi:[1,0,0]
	v_pk_fma_f32 v[168:169], v[168:169], s[32:33], 1.0 op_sel_hi:[1,0,0]
	v_pk_fma_f32 v[170:171], v[170:171], s[32:33], 1.0 op_sel_hi:[1,0,0]
	v_pk_fma_f32 v[172:173], v[172:173], s[32:33], 1.0 op_sel_hi:[1,0,0]
	v_pk_mul_f32 v[166:167], v[166:167], v[42:43]
	v_pk_mul_f32 v[168:169], v[168:169], v[44:45]
	v_pk_mul_f32 v[170:171], v[170:171], v[34:35]
	v_pk_mul_f32 v[172:173], v[172:173], v[36:37]
	v_pk_mul_f32 v[166:167], v[166:167], s[100:101] op_sel_hi:[1,0]
	v_pk_mul_f32 v[168:169], v[168:169], s[100:101] op_sel_hi:[1,0]
	v_pk_mul_f32 v[170:171], v[170:171], s[100:101] op_sel_hi:[1,0]
	v_pk_mul_f32 v[172:173], v[172:173], s[100:101] op_sel_hi:[1,0]
	v_exp_f32_e32 v166, v166
	v_exp_f32_e32 v167, v167
	v_exp_f32_e32 v168, v168
	v_exp_f32_e32 v169, v169
	v_exp_f32_e32 v170, v170
	v_exp_f32_e32 v171, v171
	v_exp_f32_e32 v172, v172
	v_exp_f32_e32 v173, v173
	v_pk_add_f32 v[166:167], v[166:167], 1.0 op_sel_hi:[1,0]
	v_pk_add_f32 v[168:169], v[168:169], 1.0 op_sel_hi:[1,0]
	v_pk_add_f32 v[170:171], v[170:171], 1.0 op_sel_hi:[1,0]
	v_pk_add_f32 v[172:173], v[172:173], 1.0 op_sel_hi:[1,0]
	v_rcp_f32_e32 v166, v166
	v_rcp_f32_e32 v167, v167
	v_rcp_f32_e32 v168, v168
	v_rcp_f32_e32 v169, v169
	v_rcp_f32_e32 v170, v170
	v_rcp_f32_e32 v171, v171
	v_rcp_f32_e32 v172, v172
	v_rcp_f32_e32 v173, v173
; DEV float silu_f(float x) { return x * __builtin_amdgcn_rcpf(1.f + __expf(-x)); }
; DEV float gelu_f(float x) { const float t = 1.5957691216f * (x + 0.044715f * x * x * x); return x * __builtin_amdgcn_rcpf(1.f + __expf(-t)); }
; DEV u32x4 pack8(const float (&f)[8]) { u32x4 w; w.x = cvt_pk_bf16(f[0], f[1]); w.y = cvt_pk_bf16(f[2], f[3]); w.z = cvt_pk_bf16(f[4], f[5]); w.w = cvt_pk_bf16(f[6], f[7]); return w; }
;     DEV void operator()(const f32x4 (&acc)[2][2][4][2], const Unit& u, int wr, int wc, int fr, int fq) const {
;     ...
;         for (int ai = 0; ai < 2; ++ai)
; #pragma unroll
;             for (int m = 0; m < 4; ++m) {
;                 const int row = row0 + ai * 128 + m * 16; float ss = 0.f; const float rstd = rstd8[ai * 4 + m];
; #pragma unroll
;                 for (int bj = 0; bj < 2; ++bj) {
;                     float v[8];
; #pragma unroll
;                     for (int n = 0; n < 2; ++n)
; #pragma unroll
;                         for (int j = 0; j < 4; ++j) { float x = acc[ai][bj][m][n][j] * rstd + sw[bj][n][j]; if (act == 1) x = silu_f(x); else if (act == 2) x = gelu_f(x); v[4 * n + j] = x; ss += x * x; }
;                     *(u32x4*)(Z + (size_t)row * ZW + col0 + bj * 128) = pack8(v);
	v_pk_mul_f32 v[42:43], v[42:43], v[166:167]
	v_pk_mul_f32 v[44:45], v[44:45], v[168:169]
	v_pk_mul_f32 v[34:35], v[34:35], v[170:171]
	v_pk_mul_f32 v[36:37], v[36:37], v[172:173]
	v_fmac_f32_e32 v189, v42, v42
	v_fmac_f32_e32 v189, v43, v43
	v_fmac_f32_e32 v189, v44, v44
	v_fmac_f32_e32 v189, v45, v45
	v_fmac_f32_e32 v189, v34, v34
	v_fmac_f32_e32 v189, v35, v35
	v_fmac_f32_e32 v189, v36, v36
	v_fmac_f32_e32 v189, v37, v37
	v_cvt_pk_bf16_f32 v166, v42, v43
	v_cvt_pk_bf16_f32 v167, v44, v45
	v_cvt_pk_bf16_f32 v168, v34, v35
	v_cvt_pk_bf16_f32 v169, v36, v37
	global_store_dwordx4 v178, v[166:169], s[46:47] offset:0
	s_nop 1
	v_pk_fma_f32 v[26:27], v[26:27], v[248:249], v[38:39] op_sel:[0,1,0]
	v_pk_fma_f32 v[28:29], v[28:29], v[248:249], v[40:41] op_sel:[0,1,0]
	v_pk_fma_f32 v[18:19], v[18:19], v[248:249], v[46:47] op_sel:[0,1,0]
	v_pk_fma_f32 v[20:21], v[20:21], v[248:249], v[48:49] op_sel:[0,1,0]
	v_pk_mul_f32 v[166:167], v[26:27], v[26:27]
	v_pk_mul_f32 v[168:169], v[28:29], v[28:29]
	v_pk_mul_f32 v[170:171], v[18:19], v[18:19]
	v_pk_mul_f32 v[172:173], v[20:21], v[20:21]
	v_pk_fma_f32 v[166:167], v[166:167], s[32:33], 1.0 op_sel_hi:[1,0,0]
	v_pk_fma_f32 v[168:169], v[168:169], s[32:33], 1.0 op_sel_hi:[1,0,0]
	v_pk_fma_f32 v[170:171], v[170:171], s[32:33], 1.0 op_sel_hi:[1,0,0]
	v_pk_fma_f32 v[172:173], v[172:173], s[32:33], 1.0 op_sel_hi:[1,0,0]
	v_pk_mul_f32 v[166:167], v[166:167], v[26:27]
	v_pk_mul_f32 v[168:169], v[168:169], v[28:29]
	v_pk_mul_f32 v[170:171], v[170:171], v[18:19]
	v_pk_mul_f32 v[172:173], v[172:173], v[20:21]
	v_pk_mul_f32 v[166:167], v[166:167], s[100:101] op_sel_hi:[1,0]
	v_pk_mul_f32 v[168:169], v[168:169], s[100:101] op_sel_hi:[1,0]
	v_pk_mul_f32 v[170:171], v[170:171], s[100:101] op_sel_hi:[1,0]
	v_pk_mul_f32 v[172:173], v[172:173], s[100:101] op_sel_hi:[1,0]
	v_exp_f32_e32 v166, v166
	v_exp_f32_e32 v167, v167
	v_exp_f32_e32 v168, v168
	v_exp_f32_e32 v169, v169
	v_exp_f32_e32 v170, v170
	v_exp_f32_e32 v171, v171
	v_exp_f32_e32 v172, v172
	v_exp_f32_e32 v173, v173
	v_pk_add_f32 v[166:167], v[166:167], 1.0 op_sel_hi:[1,0]
	v_pk_add_f32 v[168:169], v[168:169], 1.0 op_sel_hi:[1,0]
	v_pk_add_f32 v[170:171], v[170:171], 1.0 op_sel_hi:[1,0]
	v_pk_add_f32 v[172:173], v[172:173], 1.0 op_sel_hi:[1,0]
	v_rcp_f32_e32 v166, v166
	v_rcp_f32_e32 v167, v167
	v_rcp_f32_e32 v168, v168
	v_rcp_f32_e32 v169, v169
	v_rcp_f32_e32 v170, v170
	v_rcp_f32_e32 v171, v171
	v_rcp_f32_e32 v172, v172
	v_rcp_f32_e32 v173, v173
	v_pk_mul_f32 v[26:27], v[26:27], v[166:167]
	v_pk_mul_f32 v[28:29], v[28:29], v[168:169]
	v_pk_mul_f32 v[18:19], v[18:19], v[170:171]
	v_pk_mul_f32 v[20:21], v[20:21], v[172:173]
	v_fmac_f32_e32 v189, v26, v26
	v_fmac_f32_e32 v189, v27, v27
	v_fmac_f32_e32 v189, v28, v28
	v_fmac_f32_e32 v189, v29, v29
	v_fmac_f32_e32 v189, v18, v18
	v_fmac_f32_e32 v189, v19, v19
	v_fmac_f32_e32 v189, v20, v20
	v_fmac_f32_e32 v189, v21, v21
	v_cvt_pk_bf16_f32 v166, v26, v27
	v_cvt_pk_bf16_f32 v167, v28, v29
	v_cvt_pk_bf16_f32 v168, v18, v19
	v_cvt_pk_bf16_f32 v169, v20, v21
	global_store_dwordx4 v178, v[166:169], s[46:47] offset:256
	s_nop 1
	s_add_u32 s46, s48, 0xf2000
	s_addc_u32 s47, s49, 0
	v_pk_fma_f32 v[14:15], v[14:15], v[250:251], v[22:23] op_sel_hi:[1,0,1]
	v_pk_fma_f32 v[16:17], v[16:17], v[250:251], v[24:25] op_sel_hi:[1,0,1]
	v_pk_fma_f32 v[10:11], v[10:11], v[250:251], v[30:31] op_sel_hi:[1,0,1]
	v_pk_fma_f32 v[12:13], v[12:13], v[250:251], v[32:33] op_sel_hi:[1,0,1]
	v_pk_mul_f32 v[166:167], v[14:15], v[14:15]
	v_pk_mul_f32 v[168:169], v[16:17], v[16:17]
	v_pk_mul_f32 v[170:171], v[10:11], v[10:11]
	v_pk_mul_f32 v[172:173], v[12:13], v[12:13]
	v_pk_fma_f32 v[166:167], v[166:167], s[32:33], 1.0 op_sel_hi:[1,0,0]
	v_pk_fma_f32 v[168:169], v[168:169], s[32:33], 1.0 op_sel_hi:[1,0,0]
	v_pk_fma_f32 v[170:171], v[170:171], s[32:33], 1.0 op_sel_hi:[1,0,0]
	v_pk_fma_f32 v[172:173], v[172:173], s[32:33], 1.0 op_sel_hi:[1,0,0]
	v_pk_mul_f32 v[166:167], v[166:167], v[14:15]
	v_pk_mul_f32 v[168:169], v[168:169], v[16:17]
	v_pk_mul_f32 v[170:171], v[170:171], v[10:11]
	v_pk_mul_f32 v[172:173], v[172:173], v[12:13]
	v_pk_mul_f32 v[166:167], v[166:167], s[100:101] op_sel_hi:[1,0]
	v_pk_mul_f32 v[168:169], v[168:169], s[100:101] op_sel_hi:[1,0]
	v_pk_mul_f32 v[170:171], v[170:171], s[100:101] op_sel_hi:[1,0]
	v_pk_mul_f32 v[172:173], v[172:173], s[100:101] op_sel_hi:[1,0]
	v_exp_f32_e32 v166, v166
	v_exp_f32_e32 v167, v167
	v_exp_f32_e32 v168, v168
	v_exp_f32_e32 v169, v169
	v_exp_f32_e32 v170, v170
	v_exp_f32_e32 v171, v171
	v_exp_f32_e32 v172, v172
	v_exp_f32_e32 v173, v173
	v_pk_add_f32 v[166:167], v[166:167], 1.0 op_sel_hi:[1,0]
	v_pk_add_f32 v[168:169], v[168:169], 1.0 op_sel_hi:[1,0]
	v_pk_add_f32 v[170:171], v[170:171], 1.0 op_sel_hi:[1,0]
	v_pk_add_f32 v[172:173], v[172:173], 1.0 op_sel_hi:[1,0]
	v_rcp_f32_e32 v166, v166
	v_rcp_f32_e32 v167, v167
	v_rcp_f32_e32 v168, v168
	v_rcp_f32_e32 v169, v169
	v_rcp_f32_e32 v170, v170
	v_rcp_f32_e32 v171, v171
	v_rcp_f32_e32 v172, v172
	v_rcp_f32_e32 v173, v173
	v_pk_mul_f32 v[14:15], v[14:15], v[166:167]
	v_pk_mul_f32 v[16:17], v[16:17], v[168:169]
	v_pk_mul_f32 v[10:11], v[10:11], v[170:171]
	v_pk_mul_f32 v[12:13], v[12:13], v[172:173]
	v_fmac_f32_e32 v190, v14, v14
	v_fmac_f32_e32 v190, v15, v15
	v_fmac_f32_e32 v190, v16, v16
	v_fmac_f32_e32 v190, v17, v17
	v_fmac_f32_e32 v190, v10, v10
	v_fmac_f32_e32 v190, v11, v11
	v_fmac_f32_e32 v190, v12, v12
	v_fmac_f32_e32 v190, v13, v13
	v_cvt_pk_bf16_f32 v166, v14, v15
	v_cvt_pk_bf16_f32 v167, v16, v17
	v_cvt_pk_bf16_f32 v168, v10, v11
	v_cvt_pk_bf16_f32 v169, v12, v13
	global_store_dwordx4 v178, v[166:169], s[46:47] offset:0
	s_nop 1
; DEV float silu_f(float x) { return x * __builtin_amdgcn_rcpf(1.f + __expf(-x)); }
; DEV float gelu_f(float x) { const float t = 1.5957691216f * (x + 0.044715f * x * x * x); return x * __builtin_amdgcn_rcpf(1.f + __expf(-t)); }
; DEV u32x4 pack8(const float (&f)[8]) { u32x4 w; w.x = cvt_pk_bf16(f[0], f[1]); w.y = cvt_pk_bf16(f[2], f[3]); w.z = cvt_pk_bf16(f[4], f[5]); w.w = cvt_pk_bf16(f[6], f[7]); return w; }
;     DEV void operator()(const f32x4 (&acc)[2][2][4][2], const Unit& u, int wr, int wc, int fr, int fq) const {
;     ...
;         for (int ai = 0; ai < 2; ++ai)
; #pragma unroll
;             for (int m = 0; m < 4; ++m) {
;                 const int row = row0 + ai * 128 + m * 16; float ss = 0.f; const float rstd = rstd8[ai * 4 + m];
; #pragma unroll
;                 for (int bj = 0; bj < 2; ++bj) {
;                     float v[8];
; #pragma unroll
;                     for (int n = 0; n < 2; ++n)
; #pragma unroll
;                         for (int j = 0; j < 4; ++j) { float x = acc[ai][bj][m][n][j] * rstd + sw[bj][n][j]; if (act == 1) x = silu_f(x); else if (act == 2) x = gelu_f(x); v[4 * n + j] = x; ss += x * x; }
;                     *(u32x4*)(Z + (size_t)row * ZW + col0 + bj * 128) = pack8(v);
;                 }
;                 if (stat) { ss += __shfl_xor(ss, 16); ss += __shfl_xor(ss, 32); if (fq == 0) rowss[(size_t)row * 8 + (pn - 8) * 4 + wc] = ss; }
	v_pk_fma_f32 v[6:7], v[6:7], v[250:251], v[38:39] op_sel_hi:[1,0,1]
	v_pk_fma_f32 v[8:9], v[8:9], v[250:251], v[40:41] op_sel_hi:[1,0,1]
	v_pk_fma_f32 v[2:3], v[2:3], v[250:251], v[46:47] op_sel_hi:[1,0,1]
	v_pk_fma_f32 v[4:5], v[4:5], v[250:251], v[48:49] op_sel_hi:[1,0,1]
	v_pk_mul_f32 v[166:167], v[6:7], v[6:7]
	v_pk_mul_f32 v[168:169], v[8:9], v[8:9]
	v_pk_mul_f32 v[170:171], v[2:3], v[2:3]
	v_pk_mul_f32 v[172:173], v[4:5], v[4:5]
	v_pk_fma_f32 v[166:167], v[166:167], s[32:33], 1.0 op_sel_hi:[1,0,0]
	v_pk_fma_f32 v[168:169], v[168:169], s[32:33], 1.0 op_sel_hi:[1,0,0]
	v_pk_fma_f32 v[170:171], v[170:171], s[32:33], 1.0 op_sel_hi:[1,0,0]
	v_pk_fma_f32 v[172:173], v[172:173], s[32:33], 1.0 op_sel_hi:[1,0,0]
	v_pk_mul_f32 v[166:167], v[166:167], v[6:7]
	v_pk_mul_f32 v[168:169], v[168:169], v[8:9]
	v_pk_mul_f32 v[170:171], v[170:171], v[2:3]
	v_pk_mul_f32 v[172:173], v[172:173], v[4:5]
	v_pk_mul_f32 v[166:167], v[166:167], s[100:101] op_sel_hi:[1,0]
	v_pk_mul_f32 v[168:169], v[168:169], s[100:101] op_sel_hi:[1,0]
	v_pk_mul_f32 v[170:171], v[170:171], s[100:101] op_sel_hi:[1,0]
	v_pk_mul_f32 v[172:173], v[172:173], s[100:101] op_sel_hi:[1,0]
	v_exp_f32_e32 v166, v166
	v_exp_f32_e32 v167, v167
	v_exp_f32_e32 v168, v168
	v_exp_f32_e32 v169, v169
	v_exp_f32_e32 v170, v170
	v_exp_f32_e32 v171, v171
	v_exp_f32_e32 v172, v172
	v_exp_f32_e32 v173, v173
	v_pk_add_f32 v[166:167], v[166:167], 1.0 op_sel_hi:[1,0]
	v_pk_add_f32 v[168:169], v[168:169], 1.0 op_sel_hi:[1,0]
	v_pk_add_f32 v[170:171], v[170:171], 1.0 op_sel_hi:[1,0]
	v_pk_add_f32 v[172:173], v[172:173], 1.0 op_sel_hi:[1,0]
	v_rcp_f32_e32 v166, v166
	v_rcp_f32_e32 v167, v167
	v_rcp_f32_e32 v168, v168
	v_rcp_f32_e32 v169, v169
	v_rcp_f32_e32 v170, v170
	v_rcp_f32_e32 v171, v171
	v_rcp_f32_e32 v172, v172
	v_rcp_f32_e32 v173, v173
	v_pk_mul_f32 v[6:7], v[6:7], v[166:167]
	v_pk_mul_f32 v[8:9], v[8:9], v[168:169]
	v_pk_mul_f32 v[2:3], v[2:3], v[170:171]
	v_pk_mul_f32 v[4:5], v[4:5], v[172:173]
	v_fmac_f32_e32 v190, v6, v6
	v_fmac_f32_e32 v190, v7, v7
	v_fmac_f32_e32 v190, v8, v8
	v_fmac_f32_e32 v190, v9, v9
	v_fmac_f32_e32 v190, v2, v2
	v_fmac_f32_e32 v190, v3, v3
	v_fmac_f32_e32 v190, v4, v4
	v_fmac_f32_e32 v190, v5, v5
	v_cvt_pk_bf16_f32 v166, v6, v7
	v_cvt_pk_bf16_f32 v167, v8, v9
	v_cvt_pk_bf16_f32 v168, v2, v3
	v_cvt_pk_bf16_f32 v169, v4, v5
	global_store_dwordx4 v178, v[166:169], s[46:47] offset:256
	s_nop 1
	s_cmp_lt_i32 s10, 8
	s_cbranch_scc1 .Lp5_done
	v_xor_b32_e32 v180, 16, v204
	v_xor_b32_e32 v181, 32, v204
	v_lshlrev_b32_e32 v180, 2, v180
	v_lshlrev_b32_e32 v181, 2, v181
	ds_bpermute_b32 v191, v180, v183
	ds_bpermute_b32 v192, v180, v184
	ds_bpermute_b32 v193, v180, v185
	ds_bpermute_b32 v194, v180, v186
	ds_bpermute_b32 v195, v180, v187
	ds_bpermute_b32 v196, v180, v188
	ds_bpermute_b32 v197, v180, v189
	ds_bpermute_b32 v198, v180, v190
	s_waitcnt lgkmcnt(0)
	v_add_f32_e32 v183, v183, v191
	v_add_f32_e32 v184, v184, v192
	v_add_f32_e32 v185, v185, v193
	v_add_f32_e32 v186, v186, v194
	v_add_f32_e32 v187, v187, v195
	v_add_f32_e32 v188, v188, v196
	v_add_f32_e32 v189, v189, v197
	v_add_f32_e32 v190, v190, v198
	ds_bpermute_b32 v191, v181, v183
	ds_bpermute_b32 v192, v181, v184
	ds_bpermute_b32 v193, v181, v185
	ds_bpermute_b32 v194, v181, v186
	ds_bpermute_b32 v195, v181, v187
	ds_bpermute_b32 v196, v181, v188
	ds_bpermute_b32 v197, v181, v189
	ds_bpermute_b32 v198, v181, v190
	s_waitcnt lgkmcnt(0)
	v_add_f32_e32 v183, v183, v191
	v_add_f32_e32 v184, v184, v192
	v_add_f32_e32 v185, v185, v193
	v_add_f32_e32 v186, v186, v194
	v_add_f32_e32 v187, v187, v195
	v_add_f32_e32 v188, v188, v196
	v_add_f32_e32 v189, v189, v197
	v_add_f32_e32 v190, v190, v198
	v_lshlrev_b32_e32 v182, 5, v177
	s_sub_u32 s7, s10, 8
	s_lshl_b32 s7, s7, 2
	s_add_u32 s7, s7, s72
	s_lshl_b32 s7, s7, 2
	s_add_u32 s46, s88, 0x3c600000
	s_addc_u32 s47, s89, 0
	s_add_u32 s46, s46, s7
	s_addc_u32 s47, s47, 0
	v_cmp_eq_u32_e32 vcc, 0, v165
	s_nop 4
	s_and_saveexec_b64 s[100:101], vcc
	global_store_dword v182, v183, s[46:47] offset:0
	global_store_dword v182, v184, s[46:47] offset:512
	global_store_dword v182, v185, s[46:47] offset:1024
	global_store_dword v182, v186, s[46:47] offset:1536
	s_add_u32 s46, s46, 0x1000
	s_addc_u32 s47, s47, 0
	global_store_dword v182, v187, s[46:47] offset:0
	global_store_dword v182, v188, s[46:47] offset:512
	global_store_dword v182, v189, s[46:47] offset:1024
	global_store_dword v182, v190, s[46:47] offset:1536
	s_or_b64 exec, exec, s[100:101]
	s_branch .Lp5_done
; DEV float silu_f(float x) { return x * __builtin_amdgcn_rcpf(1.f + __expf(-x)); }
; DEV float gelu_f(float x) { const float t = 1.5957691216f * (x + 0.044715f * x * x * x); return x * __builtin_amdgcn_rcpf(1.f + __expf(-t)); }
; DEV u32x4 pack8(const float (&f)[8]) { u32x4 w; w.x = cvt_pk_bf16(f[0], f[1]); w.y = cvt_pk_bf16(f[2], f[3]); w.z = cvt_pk_bf16(f[4], f[5]); w.w = cvt_pk_bf16(f[6], f[7]); return w; }
;     DEV void operator()(const f32x4 (&acc)[2][2][4][2], const Unit& u, int wr, int wc, int fr, int fq) const {
;     ...
;         for (int ai = 0; ai < 2; ++ai)
; #pragma unroll
;             for (int m = 0; m < 4; ++m) {
;                 const int row = row0 + ai * 128 + m * 16; float ss = 0.f; const float rstd = rstd8[ai * 4 + m];
; #pragma unroll
;                 for (int bj = 0; bj < 2; ++bj) {
;                     float v[8];
; #pragma unroll
;                     for (int n = 0; n < 2; ++n)
; #pragma unroll
;                         for (int j = 0; j < 4; ++j) { float x = acc[ai][bj][m][n][j] * rstd + sw[bj][n][j]; if (act == 1) x = silu_f(x); else if (act == 2) x = gelu_f(x); v[4 * n + j] = x; ss += x * x; }
;                     *(u32x4*)(Z + (size_t)row * ZW + col0 + bj * 128) = pack8(v);
.Lp5_act1:
	s_mov_b32 s100, 0xbfb8aa3b
	v_pk_fma_f32 v[142:143], v[142:143], v[242:243], v[22:23] op_sel:[0,1,0]
	v_pk_fma_f32 v[144:145], v[144:145], v[242:243], v[24:25] op_sel:[0,1,0]
	v_pk_fma_f32 v[138:139], v[138:139], v[242:243], v[30:31] op_sel:[0,1,0]
	v_pk_fma_f32 v[140:141], v[140:141], v[242:243], v[32:33] op_sel:[0,1,0]
	v_pk_mul_f32 v[166:167], v[142:143], s[100:101] op_sel_hi:[1,0]
	v_pk_mul_f32 v[168:169], v[144:145], s[100:101] op_sel_hi:[1,0]
	v_pk_mul_f32 v[170:171], v[138:139], s[100:101] op_sel_hi:[1,0]
	v_pk_mul_f32 v[172:173], v[140:141], s[100:101] op_sel_hi:[1,0]
	v_exp_f32_e32 v166, v166
	v_exp_f32_e32 v167, v167
	v_exp_f32_e32 v168, v168
	v_exp_f32_e32 v169, v169
	v_exp_f32_e32 v170, v170
	v_exp_f32_e32 v171, v171
	v_exp_f32_e32 v172, v172
	v_exp_f32_e32 v173, v173
	v_pk_add_f32 v[166:167], v[166:167], 1.0 op_sel_hi:[1,0]
	v_pk_add_f32 v[168:169], v[168:169], 1.0 op_sel_hi:[1,0]
	v_pk_add_f32 v[170:171], v[170:171], 1.0 op_sel_hi:[1,0]
	v_pk_add_f32 v[172:173], v[172:173], 1.0 op_sel_hi:[1,0]
	v_rcp_f32_e32 v166, v166
	v_rcp_f32_e32 v167, v167
	v_rcp_f32_e32 v168, v168
	v_rcp_f32_e32 v169, v169
	v_rcp_f32_e32 v170, v170
	v_rcp_f32_e32 v171, v171
	v_rcp_f32_e32 v172, v172
	v_rcp_f32_e32 v173, v173
	v_pk_mul_f32 v[142:143], v[142:143], v[166:167]
	v_pk_mul_f32 v[144:145], v[144:145], v[168:169]
	v_pk_mul_f32 v[138:139], v[138:139], v[170:171]
	v_pk_mul_f32 v[140:141], v[140:141], v[172:173]
	v_cvt_pk_bf16_f32 v166, v142, v143
	v_cvt_pk_bf16_f32 v167, v144, v145
	v_cvt_pk_bf16_f32 v168, v138, v139
	v_cvt_pk_bf16_f32 v169, v140, v141
	global_store_dwordx4 v178, v[166:169], s[48:49] offset:0
	s_nop 1
	v_pk_fma_f32 v[134:135], v[134:135], v[242:243], v[38:39] op_sel:[0,1,0]
	v_pk_fma_f32 v[136:137], v[136:137], v[242:243], v[40:41] op_sel:[0,1,0]
	v_pk_fma_f32 v[130:131], v[130:131], v[242:243], v[46:47] op_sel:[0,1,0]
	v_pk_fma_f32 v[132:133], v[132:133], v[242:243], v[48:49] op_sel:[0,1,0]
	v_pk_mul_f32 v[166:167], v[134:135], s[100:101] op_sel_hi:[1,0]
	v_pk_mul_f32 v[168:169], v[136:137], s[100:101] op_sel_hi:[1,0]
	v_pk_mul_f32 v[170:171], v[130:131], s[100:101] op_sel_hi:[1,0]
	v_pk_mul_f32 v[172:173], v[132:133], s[100:101] op_sel_hi:[1,0]
	v_exp_f32_e32 v166, v166
	v_exp_f32_e32 v167, v167
	v_exp_f32_e32 v168, v168
	v_exp_f32_e32 v169, v169
	v_exp_f32_e32 v170, v170
	v_exp_f32_e32 v171, v171
	v_exp_f32_e32 v172, v172
	v_exp_f32_e32 v173, v173
	v_pk_add_f32 v[166:167], v[166:167], 1.0 op_sel_hi:[1,0]
	v_pk_add_f32 v[168:169], v[168:169], 1.0 op_sel_hi:[1,0]
	v_pk_add_f32 v[170:171], v[170:171], 1.0 op_sel_hi:[1,0]
	v_pk_add_f32 v[172:173], v[172:173], 1.0 op_sel_hi:[1,0]
	v_rcp_f32_e32 v166, v166
	v_rcp_f32_e32 v167, v167
	v_rcp_f32_e32 v168, v168
	v_rcp_f32_e32 v169, v169
	v_rcp_f32_e32 v170, v170
	v_rcp_f32_e32 v171, v171
	v_rcp_f32_e32 v172, v172
	v_rcp_f32_e32 v173, v173
	v_pk_mul_f32 v[134:135], v[134:135], v[166:167]
	v_pk_mul_f32 v[136:137], v[136:137], v[168:169]
	v_pk_mul_f32 v[130:131], v[130:131], v[170:171]
	v_pk_mul_f32 v[132:133], v[132:133], v[172:173]
	v_cvt_pk_bf16_f32 v166, v134, v135
	v_cvt_pk_bf16_f32 v167, v136, v137
	v_cvt_pk_bf16_f32 v168, v130, v131
	v_cvt_pk_bf16_f32 v169, v132, v133
	global_store_dwordx4 v178, v[166:169], s[48:49] offset:256
	s_nop 1
	s_add_u32 s46, s48, 0x16000
	s_addc_u32 s47, s49, 0
	v_pk_fma_f32 v[126:127], v[126:127], v[244:245], v[22:23] op_sel_hi:[1,0,1]
	v_pk_fma_f32 v[128:129], v[128:129], v[244:245], v[24:25] op_sel_hi:[1,0,1]
	v_pk_fma_f32 v[122:123], v[122:123], v[244:245], v[30:31] op_sel_hi:[1,0,1]
	v_pk_fma_f32 v[124:125], v[124:125], v[244:245], v[32:33] op_sel_hi:[1,0,1]
	v_pk_mul_f32 v[166:167], v[126:127], s[100:101] op_sel_hi:[1,0]
	v_pk_mul_f32 v[168:169], v[128:129], s[100:101] op_sel_hi:[1,0]
	v_pk_mul_f32 v[170:171], v[122:123], s[100:101] op_sel_hi:[1,0]
	v_pk_mul_f32 v[172:173], v[124:125], s[100:101] op_sel_hi:[1,0]
	v_exp_f32_e32 v166, v166
	v_exp_f32_e32 v167, v167
	v_exp_f32_e32 v168, v168
	v_exp_f32_e32 v169, v169
	v_exp_f32_e32 v170, v170
	v_exp_f32_e32 v171, v171
	v_exp_f32_e32 v172, v172
	v_exp_f32_e32 v173, v173
	v_pk_add_f32 v[166:167], v[166:167], 1.0 op_sel_hi:[1,0]
	v_pk_add_f32 v[168:169], v[168:169], 1.0 op_sel_hi:[1,0]
	v_pk_add_f32 v[170:171], v[170:171], 1.0 op_sel_hi:[1,0]
	v_pk_add_f32 v[172:173], v[172:173], 1.0 op_sel_hi:[1,0]
	v_rcp_f32_e32 v166, v166
	v_rcp_f32_e32 v167, v167
	v_rcp_f32_e32 v168, v168
	v_rcp_f32_e32 v169, v169
	v_rcp_f32_e32 v170, v170
	v_rcp_f32_e32 v171, v171
	v_rcp_f32_e32 v172, v172
	v_rcp_f32_e32 v173, v173
	v_pk_mul_f32 v[126:127], v[126:127], v[166:167]
	v_pk_mul_f32 v[128:129], v[128:129], v[168:169]
	v_pk_mul_f32 v[122:123], v[122:123], v[170:171]
	v_pk_mul_f32 v[124:125], v[124:125], v[172:173]
	v_cvt_pk_bf16_f32 v166, v126, v127
	v_cvt_pk_bf16_f32 v167, v128, v129
	v_cvt_pk_bf16_f32 v168, v122, v123
	v_cvt_pk_bf16_f32 v169, v124, v125
	global_store_dwordx4 v178, v[166:169], s[46:47] offset:0
	s_nop 1
	v_pk_fma_f32 v[118:119], v[118:119], v[244:245], v[38:39] op_sel_hi:[1,0,1]
	v_pk_fma_f32 v[120:121], v[120:121], v[244:245], v[40:41] op_sel_hi:[1,0,1]
	v_pk_fma_f32 v[114:115], v[114:115], v[244:245], v[46:47] op_sel_hi:[1,0,1]
	v_pk_fma_f32 v[116:117], v[116:117], v[244:245], v[48:49] op_sel_hi:[1,0,1]
	v_pk_mul_f32 v[166:167], v[118:119], s[100:101] op_sel_hi:[1,0]
	v_pk_mul_f32 v[168:169], v[120:121], s[100:101] op_sel_hi:[1,0]
	v_pk_mul_f32 v[170:171], v[114:115], s[100:101] op_sel_hi:[1,0]
	v_pk_mul_f32 v[172:173], v[116:117], s[100:101] op_sel_hi:[1,0]
	v_exp_f32_e32 v166, v166
	v_exp_f32_e32 v167, v167
	v_exp_f32_e32 v168, v168
	v_exp_f32_e32 v169, v169
	v_exp_f32_e32 v170, v170
; DEV float silu_f(float x) { return x * __builtin_amdgcn_rcpf(1.f + __expf(-x)); }
; DEV float gelu_f(float x) { const float t = 1.5957691216f * (x + 0.044715f * x * x * x); return x * __builtin_amdgcn_rcpf(1.f + __expf(-t)); }
; DEV u32x4 pack8(const float (&f)[8]) { u32x4 w; w.x = cvt_pk_bf16(f[0], f[1]); w.y = cvt_pk_bf16(f[2], f[3]); w.z = cvt_pk_bf16(f[4], f[5]); w.w = cvt_pk_bf16(f[6], f[7]); return w; }
;     DEV void operator()(const f32x4 (&acc)[2][2][4][2], const Unit& u, int wr, int wc, int fr, int fq) const {
;     ...
;         for (int ai = 0; ai < 2; ++ai)
; #pragma unroll
;             for (int m = 0; m < 4; ++m) {
;                 const int row = row0 + ai * 128 + m * 16; float ss = 0.f; const float rstd = rstd8[ai * 4 + m];
; #pragma unroll
;                 for (int bj = 0; bj < 2; ++bj) {
;                     float v[8];
; #pragma unroll
;                     for (int n = 0; n < 2; ++n)
; #pragma unroll
;                         for (int j = 0; j < 4; ++j) { float x = acc[ai][bj][m][n][j] * rstd + sw[bj][n][j]; if (act == 1) x = silu_f(x); else if (act == 2) x = gelu_f(x); v[4 * n + j] = x; ss += x * x; }
;                     *(u32x4*)(Z + (size_t)row * ZW + col0 + bj * 128) = pack8(v);
	v_exp_f32_e32 v171, v171
	v_exp_f32_e32 v172, v172
	v_exp_f32_e32 v173, v173
	v_pk_add_f32 v[166:167], v[166:167], 1.0 op_sel_hi:[1,0]
	v_pk_add_f32 v[168:169], v[168:169], 1.0 op_sel_hi:[1,0]
	v_pk_add_f32 v[170:171], v[170:171], 1.0 op_sel_hi:[1,0]
	v_pk_add_f32 v[172:173], v[172:173], 1.0 op_sel_hi:[1,0]
	v_rcp_f32_e32 v166, v166
	v_rcp_f32_e32 v167, v167
	v_rcp_f32_e32 v168, v168
	v_rcp_f32_e32 v169, v169
	v_rcp_f32_e32 v170, v170
	v_rcp_f32_e32 v171, v171
	v_rcp_f32_e32 v172, v172
	v_rcp_f32_e32 v173, v173
	v_pk_mul_f32 v[118:119], v[118:119], v[166:167]
	v_pk_mul_f32 v[120:121], v[120:121], v[168:169]
	v_pk_mul_f32 v[114:115], v[114:115], v[170:171]
	v_pk_mul_f32 v[116:117], v[116:117], v[172:173]
	v_cvt_pk_bf16_f32 v166, v118, v119
	v_cvt_pk_bf16_f32 v167, v120, v121
	v_cvt_pk_bf16_f32 v168, v114, v115
	v_cvt_pk_bf16_f32 v169, v116, v117
	global_store_dwordx4 v178, v[166:169], s[46:47] offset:256
	s_nop 1
	s_add_u32 s46, s48, 0x2c000
	s_addc_u32 s47, s49, 0
	v_pk_fma_f32 v[110:111], v[110:111], v[244:245], v[22:23] op_sel:[0,1,0]
	v_pk_fma_f32 v[112:113], v[112:113], v[244:245], v[24:25] op_sel:[0,1,0]
	v_pk_fma_f32 v[106:107], v[106:107], v[244:245], v[30:31] op_sel:[0,1,0]
	v_pk_fma_f32 v[108:109], v[108:109], v[244:245], v[32:33] op_sel:[0,1,0]
	v_pk_mul_f32 v[166:167], v[110:111], s[100:101] op_sel_hi:[1,0]
	v_pk_mul_f32 v[168:169], v[112:113], s[100:101] op_sel_hi:[1,0]
	v_pk_mul_f32 v[170:171], v[106:107], s[100:101] op_sel_hi:[1,0]
	v_pk_mul_f32 v[172:173], v[108:109], s[100:101] op_sel_hi:[1,0]
	v_exp_f32_e32 v166, v166
	v_exp_f32_e32 v167, v167
	v_exp_f32_e32 v168, v168
	v_exp_f32_e32 v169, v169
	v_exp_f32_e32 v170, v170
	v_exp_f32_e32 v171, v171
	v_exp_f32_e32 v172, v172
	v_exp_f32_e32 v173, v173
	v_pk_add_f32 v[166:167], v[166:167], 1.0 op_sel_hi:[1,0]
	v_pk_add_f32 v[168:169], v[168:169], 1.0 op_sel_hi:[1,0]
	v_pk_add_f32 v[170:171], v[170:171], 1.0 op_sel_hi:[1,0]
	v_pk_add_f32 v[172:173], v[172:173], 1.0 op_sel_hi:[1,0]
	v_rcp_f32_e32 v166, v166
	v_rcp_f32_e32 v167, v167
	v_rcp_f32_e32 v168, v168
	v_rcp_f32_e32 v169, v169
	v_rcp_f32_e32 v170, v170
	v_rcp_f32_e32 v171, v171
	v_rcp_f32_e32 v172, v172
	v_rcp_f32_e32 v173, v173
	v_pk_mul_f32 v[110:111], v[110:111], v[166:167]
	v_pk_mul_f32 v[112:113], v[112:113], v[168:169]
	v_pk_mul_f32 v[106:107], v[106:107], v[170:171]
	v_pk_mul_f32 v[108:109], v[108:109], v[172:173]
	v_cvt_pk_bf16_f32 v166, v110, v111
	v_cvt_pk_bf16_f32 v167, v112, v113
	v_cvt_pk_bf16_f32 v168, v106, v107
	v_cvt_pk_bf16_f32 v169, v108, v109
	global_store_dwordx4 v178, v[166:169], s[46:47] offset:0
	s_nop 1
	v_pk_fma_f32 v[102:103], v[102:103], v[244:245], v[38:39] op_sel:[0,1,0]
	v_pk_fma_f32 v[104:105], v[104:105], v[244:245], v[40:41] op_sel:[0,1,0]
	v_pk_fma_f32 v[98:99], v[98:99], v[244:245], v[46:47] op_sel:[0,1,0]
	v_pk_fma_f32 v[100:101], v[100:101], v[244:245], v[48:49] op_sel:[0,1,0]
	v_pk_mul_f32 v[166:167], v[102:103], s[100:101] op_sel_hi:[1,0]
	v_pk_mul_f32 v[168:169], v[104:105], s[100:101] op_sel_hi:[1,0]
	v_pk_mul_f32 v[170:171], v[98:99], s[100:101] op_sel_hi:[1,0]
	v_pk_mul_f32 v[172:173], v[100:101], s[100:101] op_sel_hi:[1,0]
	v_exp_f32_e32 v166, v166
	v_exp_f32_e32 v167, v167
	v_exp_f32_e32 v168, v168
	v_exp_f32_e32 v169, v169
	v_exp_f32_e32 v170, v170
	v_exp_f32_e32 v171, v171
	v_exp_f32_e32 v172, v172
	v_exp_f32_e32 v173, v173
	v_pk_add_f32 v[166:167], v[166:167], 1.0 op_sel_hi:[1,0]
	v_pk_add_f32 v[168:169], v[168:169], 1.0 op_sel_hi:[1,0]
	v_pk_add_f32 v[170:171], v[170:171], 1.0 op_sel_hi:[1,0]
	v_pk_add_f32 v[172:173], v[172:173], 1.0 op_sel_hi:[1,0]
	v_rcp_f32_e32 v166, v166
	v_rcp_f32_e32 v167, v167
	v_rcp_f32_e32 v168, v168
	v_rcp_f32_e32 v169, v169
	v_rcp_f32_e32 v170, v170
	v_rcp_f32_e32 v171, v171
	v_rcp_f32_e32 v172, v172
	v_rcp_f32_e32 v173, v173
	v_pk_mul_f32 v[102:103], v[102:103], v[166:167]
	v_pk_mul_f32 v[104:105], v[104:105], v[168:169]
	v_pk_mul_f32 v[98:99], v[98:99], v[170:171]
	v_pk_mul_f32 v[100:101], v[100:101], v[172:173]
	v_cvt_pk_bf16_f32 v166, v102, v103
	v_cvt_pk_bf16_f32 v167, v104, v105
	v_cvt_pk_bf16_f32 v168, v98, v99
	v_cvt_pk_bf16_f32 v169, v100, v101
	global_store_dwordx4 v178, v[166:169], s[46:47] offset:256
	s_nop 1
	s_add_u32 s46, s48, 0x42000
	s_addc_u32 s47, s49, 0
	v_pk_fma_f32 v[94:95], v[94:95], v[246:247], v[22:23] op_sel_hi:[1,0,1]
	v_pk_fma_f32 v[96:97], v[96:97], v[246:247], v[24:25] op_sel_hi:[1,0,1]
	v_pk_fma_f32 v[90:91], v[90:91], v[246:247], v[30:31] op_sel_hi:[1,0,1]
	v_pk_fma_f32 v[92:93], v[92:93], v[246:247], v[32:33] op_sel_hi:[1,0,1]
	v_pk_mul_f32 v[166:167], v[94:95], s[100:101] op_sel_hi:[1,0]
	v_pk_mul_f32 v[168:169], v[96:97], s[100:101] op_sel_hi:[1,0]
	v_pk_mul_f32 v[170:171], v[90:91], s[100:101] op_sel_hi:[1,0]
	v_pk_mul_f32 v[172:173], v[92:93], s[100:101] op_sel_hi:[1,0]
	v_exp_f32_e32 v166, v166
	v_exp_f32_e32 v167, v167
	v_exp_f32_e32 v168, v168
	v_exp_f32_e32 v169, v169
	v_exp_f32_e32 v170, v170
	v_exp_f32_e32 v171, v171
	v_exp_f32_e32 v172, v172
	v_exp_f32_e32 v173, v173
	v_pk_add_f32 v[166:167], v[166:167], 1.0 op_sel_hi:[1,0]
	v_pk_add_f32 v[168:169], v[168:169], 1.0 op_sel_hi:[1,0]
	v_pk_add_f32 v[170:171], v[170:171], 1.0 op_sel_hi:[1,0]
	v_pk_add_f32 v[172:173], v[172:173], 1.0 op_sel_hi:[1,0]
	v_rcp_f32_e32 v166, v166
	v_rcp_f32_e32 v167, v167
	v_rcp_f32_e32 v168, v168
	v_rcp_f32_e32 v169, v169
	v_rcp_f32_e32 v170, v170
	v_rcp_f32_e32 v171, v171
	v_rcp_f32_e32 v172, v172
	v_rcp_f32_e32 v173, v173
	v_pk_mul_f32 v[94:95], v[94:95], v[166:167]
	v_pk_mul_f32 v[96:97], v[96:97], v[168:169]
	v_pk_mul_f32 v[90:91], v[90:91], v[170:171]
	v_pk_mul_f32 v[92:93], v[92:93], v[172:173]
	v_cvt_pk_bf16_f32 v166, v94, v95
; DEV float gelu_f(float x) { const float t = 1.5957691216f * (x + 0.044715f * x * x * x); return x * __builtin_amdgcn_rcpf(1.f + __expf(-t)); }
; DEV u32x4 pack8(const float (&f)[8]) { u32x4 w; w.x = cvt_pk_bf16(f[0], f[1]); w.y = cvt_pk_bf16(f[2], f[3]); w.z = cvt_pk_bf16(f[4], f[5]); w.w = cvt_pk_bf16(f[6], f[7]); return w; }
; DEV float silu_f(float x) { return x * __builtin_amdgcn_rcpf(1.f + __expf(-x)); }
;     DEV void operator()(const f32x4 (&acc)[2][2][4][2], const Unit& u, int wr, int wc, int fr, int fq) const {
;     ...
;         for (int ai = 0; ai < 2; ++ai)
; #pragma unroll
;             for (int m = 0; m < 4; ++m) {
;                 const int row = row0 + ai * 128 + m * 16; float ss = 0.f; const float rstd = rstd8[ai * 4 + m];
; #pragma unroll
;                 for (int bj = 0; bj < 2; ++bj) {
;                     float v[8];
; #pragma unroll
;                     for (int n = 0; n < 2; ++n)
; #pragma unroll
;                         for (int j = 0; j < 4; ++j) { float x = acc[ai][bj][m][n][j] * rstd + sw[bj][n][j]; if (act == 1) x = silu_f(x); else if (act == 2) x = gelu_f(x); v[4 * n + j] = x; ss += x * x; }
;                     *(u32x4*)(Z + (size_t)row * ZW + col0 + bj * 128) = pack8(v);
	v_cvt_pk_bf16_f32 v167, v96, v97
	v_cvt_pk_bf16_f32 v168, v90, v91
	v_cvt_pk_bf16_f32 v169, v92, v93
	global_store_dwordx4 v178, v[166:169], s[46:47] offset:0
	s_nop 1
	v_pk_fma_f32 v[86:87], v[86:87], v[246:247], v[38:39] op_sel_hi:[1,0,1]
	v_pk_fma_f32 v[88:89], v[88:89], v[246:247], v[40:41] op_sel_hi:[1,0,1]
	v_pk_fma_f32 v[82:83], v[82:83], v[246:247], v[46:47] op_sel_hi:[1,0,1]
	v_pk_fma_f32 v[84:85], v[84:85], v[246:247], v[48:49] op_sel_hi:[1,0,1]
	v_pk_mul_f32 v[166:167], v[86:87], s[100:101] op_sel_hi:[1,0]
	v_pk_mul_f32 v[168:169], v[88:89], s[100:101] op_sel_hi:[1,0]
	v_pk_mul_f32 v[170:171], v[82:83], s[100:101] op_sel_hi:[1,0]
	v_pk_mul_f32 v[172:173], v[84:85], s[100:101] op_sel_hi:[1,0]
	v_exp_f32_e32 v166, v166
	v_exp_f32_e32 v167, v167
	v_exp_f32_e32 v168, v168
	v_exp_f32_e32 v169, v169
	v_exp_f32_e32 v170, v170
	v_exp_f32_e32 v171, v171
	v_exp_f32_e32 v172, v172
	v_exp_f32_e32 v173, v173
	v_pk_add_f32 v[166:167], v[166:167], 1.0 op_sel_hi:[1,0]
	v_pk_add_f32 v[168:169], v[168:169], 1.0 op_sel_hi:[1,0]
	v_pk_add_f32 v[170:171], v[170:171], 1.0 op_sel_hi:[1,0]
	v_pk_add_f32 v[172:173], v[172:173], 1.0 op_sel_hi:[1,0]
	v_rcp_f32_e32 v166, v166
	v_rcp_f32_e32 v167, v167
	v_rcp_f32_e32 v168, v168
	v_rcp_f32_e32 v169, v169
	v_rcp_f32_e32 v170, v170
	v_rcp_f32_e32 v171, v171
	v_rcp_f32_e32 v172, v172
	v_rcp_f32_e32 v173, v173
	v_pk_mul_f32 v[86:87], v[86:87], v[166:167]
	v_pk_mul_f32 v[88:89], v[88:89], v[168:169]
	v_pk_mul_f32 v[82:83], v[82:83], v[170:171]
	v_pk_mul_f32 v[84:85], v[84:85], v[172:173]
	v_cvt_pk_bf16_f32 v166, v86, v87
	v_cvt_pk_bf16_f32 v167, v88, v89
	v_cvt_pk_bf16_f32 v168, v82, v83
	v_cvt_pk_bf16_f32 v169, v84, v85
	global_store_dwordx4 v178, v[166:169], s[46:47] offset:256
	s_nop 1
	s_add_u32 s46, s48, 0xb0000
	s_addc_u32 s47, s49, 0
	v_pk_fma_f32 v[78:79], v[78:79], v[246:247], v[22:23] op_sel:[0,1,0]
	v_pk_fma_f32 v[80:81], v[80:81], v[246:247], v[24:25] op_sel:[0,1,0]
	v_pk_fma_f32 v[74:75], v[74:75], v[246:247], v[30:31] op_sel:[0,1,0]
	v_pk_fma_f32 v[76:77], v[76:77], v[246:247], v[32:33] op_sel:[0,1,0]
	v_pk_mul_f32 v[166:167], v[78:79], s[100:101] op_sel_hi:[1,0]
	v_pk_mul_f32 v[168:169], v[80:81], s[100:101] op_sel_hi:[1,0]
	v_pk_mul_f32 v[170:171], v[74:75], s[100:101] op_sel_hi:[1,0]
	v_pk_mul_f32 v[172:173], v[76:77], s[100:101] op_sel_hi:[1,0]
	v_exp_f32_e32 v166, v166
	v_exp_f32_e32 v167, v167
	v_exp_f32_e32 v168, v168
	v_exp_f32_e32 v169, v169
	v_exp_f32_e32 v170, v170
	v_exp_f32_e32 v171, v171
	v_exp_f32_e32 v172, v172
	v_exp_f32_e32 v173, v173
	v_pk_add_f32 v[166:167], v[166:167], 1.0 op_sel_hi:[1,0]
	v_pk_add_f32 v[168:169], v[168:169], 1.0 op_sel_hi:[1,0]
	v_pk_add_f32 v[170:171], v[170:171], 1.0 op_sel_hi:[1,0]
	v_pk_add_f32 v[172:173], v[172:173], 1.0 op_sel_hi:[1,0]
	v_rcp_f32_e32 v166, v166
	v_rcp_f32_e32 v167, v167
	v_rcp_f32_e32 v168, v168
	v_rcp_f32_e32 v169, v169
	v_rcp_f32_e32 v170, v170
	v_rcp_f32_e32 v171, v171
	v_rcp_f32_e32 v172, v172
	v_rcp_f32_e32 v173, v173
	v_pk_mul_f32 v[78:79], v[78:79], v[166:167]
	v_pk_mul_f32 v[80:81], v[80:81], v[168:169]
	v_pk_mul_f32 v[74:75], v[74:75], v[170:171]
	v_pk_mul_f32 v[76:77], v[76:77], v[172:173]
	v_cvt_pk_bf16_f32 v166, v78, v79
	v_cvt_pk_bf16_f32 v167, v80, v81
	v_cvt_pk_bf16_f32 v168, v74, v75
	v_cvt_pk_bf16_f32 v169, v76, v77
	global_store_dwordx4 v178, v[166:169], s[46:47] offset:0
	s_nop 1
	v_pk_fma_f32 v[70:71], v[70:71], v[246:247], v[38:39] op_sel:[0,1,0]
	v_pk_fma_f32 v[72:73], v[72:73], v[246:247], v[40:41] op_sel:[0,1,0]
	v_pk_fma_f32 v[66:67], v[66:67], v[246:247], v[46:47] op_sel:[0,1,0]
	v_pk_fma_f32 v[68:69], v[68:69], v[246:247], v[48:49] op_sel:[0,1,0]
	v_pk_mul_f32 v[166:167], v[70:71], s[100:101] op_sel_hi:[1,0]
	v_pk_mul_f32 v[168:169], v[72:73], s[100:101] op_sel_hi:[1,0]
	v_pk_mul_f32 v[170:171], v[66:67], s[100:101] op_sel_hi:[1,0]
	v_pk_mul_f32 v[172:173], v[68:69], s[100:101] op_sel_hi:[1,0]
	v_exp_f32_e32 v166, v166
	v_exp_f32_e32 v167, v167
	v_exp_f32_e32 v168, v168
	v_exp_f32_e32 v169, v169
	v_exp_f32_e32 v170, v170
	v_exp_f32_e32 v171, v171
	v_exp_f32_e32 v172, v172
	v_exp_f32_e32 v173, v173
	v_pk_add_f32 v[166:167], v[166:167], 1.0 op_sel_hi:[1,0]
	v_pk_add_f32 v[168:169], v[168:169], 1.0 op_sel_hi:[1,0]
	v_pk_add_f32 v[170:171], v[170:171], 1.0 op_sel_hi:[1,0]
	v_pk_add_f32 v[172:173], v[172:173], 1.0 op_sel_hi:[1,0]
	v_rcp_f32_e32 v166, v166
	v_rcp_f32_e32 v167, v167
	v_rcp_f32_e32 v168, v168
	v_rcp_f32_e32 v169, v169
	v_rcp_f32_e32 v170, v170
	v_rcp_f32_e32 v171, v171
	v_rcp_f32_e32 v172, v172
	v_rcp_f32_e32 v173, v173
	v_pk_mul_f32 v[70:71], v[70:71], v[166:167]
	v_pk_mul_f32 v[72:73], v[72:73], v[168:169]
	v_pk_mul_f32 v[66:67], v[66:67], v[170:171]
	v_pk_mul_f32 v[68:69], v[68:69], v[172:173]
	v_cvt_pk_bf16_f32 v166, v70, v71
	v_cvt_pk_bf16_f32 v167, v72, v73
	v_cvt_pk_bf16_f32 v168, v66, v67
	v_cvt_pk_bf16_f32 v169, v68, v69
	global_store_dwordx4 v178, v[166:169], s[46:47] offset:256
	s_nop 1
	s_add_u32 s46, s48, 0xc6000
	s_addc_u32 s47, s49, 0
	v_pk_fma_f32 v[62:63], v[62:63], v[248:249], v[22:23] op_sel_hi:[1,0,1]
	v_pk_fma_f32 v[64:65], v[64:65], v[248:249], v[24:25] op_sel_hi:[1,0,1]
	v_pk_fma_f32 v[58:59], v[58:59], v[248:249], v[30:31] op_sel_hi:[1,0,1]
	v_pk_fma_f32 v[60:61], v[60:61], v[248:249], v[32:33] op_sel_hi:[1,0,1]
	v_pk_mul_f32 v[166:167], v[62:63], s[100:101] op_sel_hi:[1,0]
	v_pk_mul_f32 v[168:169], v[64:65], s[100:101] op_sel_hi:[1,0]
	v_pk_mul_f32 v[170:171], v[58:59], s[100:101] op_sel_hi:[1,0]
	v_pk_mul_f32 v[172:173], v[60:61], s[100:101] op_sel_hi:[1,0]
	v_exp_f32_e32 v166, v166
	v_exp_f32_e32 v167, v167
	v_exp_f32_e32 v168, v168
	v_exp_f32_e32 v169, v169
; DEV float gelu_f(float x) { const float t = 1.5957691216f * (x + 0.044715f * x * x * x); return x * __builtin_amdgcn_rcpf(1.f + __expf(-t)); }
; DEV u32x4 pack8(const float (&f)[8]) { u32x4 w; w.x = cvt_pk_bf16(f[0], f[1]); w.y = cvt_pk_bf16(f[2], f[3]); w.z = cvt_pk_bf16(f[4], f[5]); w.w = cvt_pk_bf16(f[6], f[7]); return w; }
; DEV float silu_f(float x) { return x * __builtin_amdgcn_rcpf(1.f + __expf(-x)); }
;     DEV void operator()(const f32x4 (&acc)[2][2][4][2], const Unit& u, int wr, int wc, int fr, int fq) const {
;     ...
;         for (int ai = 0; ai < 2; ++ai)
; #pragma unroll
;             for (int m = 0; m < 4; ++m) {
;                 const int row = row0 + ai * 128 + m * 16; float ss = 0.f; const float rstd = rstd8[ai * 4 + m];
; #pragma unroll
;                 for (int bj = 0; bj < 2; ++bj) {
;                     float v[8];
; #pragma unroll
;                     for (int n = 0; n < 2; ++n)
; #pragma unroll
;                         for (int j = 0; j < 4; ++j) { float x = acc[ai][bj][m][n][j] * rstd + sw[bj][n][j]; if (act == 1) x = silu_f(x); else if (act == 2) x = gelu_f(x); v[4 * n + j] = x; ss += x * x; }
;                     *(u32x4*)(Z + (size_t)row * ZW + col0 + bj * 128) = pack8(v);
	v_exp_f32_e32 v170, v170
	v_exp_f32_e32 v171, v171
	v_exp_f32_e32 v172, v172
	v_exp_f32_e32 v173, v173
	v_pk_add_f32 v[166:167], v[166:167], 1.0 op_sel_hi:[1,0]
	v_pk_add_f32 v[168:169], v[168:169], 1.0 op_sel_hi:[1,0]
	v_pk_add_f32 v[170:171], v[170:171], 1.0 op_sel_hi:[1,0]
	v_pk_add_f32 v[172:173], v[172:173], 1.0 op_sel_hi:[1,0]
	v_rcp_f32_e32 v166, v166
	v_rcp_f32_e32 v167, v167
	v_rcp_f32_e32 v168, v168
	v_rcp_f32_e32 v169, v169
	v_rcp_f32_e32 v170, v170
	v_rcp_f32_e32 v171, v171
	v_rcp_f32_e32 v172, v172
	v_rcp_f32_e32 v173, v173
	v_pk_mul_f32 v[62:63], v[62:63], v[166:167]
	v_pk_mul_f32 v[64:65], v[64:65], v[168:169]
	v_pk_mul_f32 v[58:59], v[58:59], v[170:171]
	v_pk_mul_f32 v[60:61], v[60:61], v[172:173]
	v_cvt_pk_bf16_f32 v166, v62, v63
	v_cvt_pk_bf16_f32 v167, v64, v65
	v_cvt_pk_bf16_f32 v168, v58, v59
	v_cvt_pk_bf16_f32 v169, v60, v61
	global_store_dwordx4 v178, v[166:169], s[46:47] offset:0
	s_nop 1
	v_pk_fma_f32 v[54:55], v[54:55], v[248:249], v[38:39] op_sel_hi:[1,0,1]
	v_pk_fma_f32 v[56:57], v[56:57], v[248:249], v[40:41] op_sel_hi:[1,0,1]
	v_pk_fma_f32 v[50:51], v[50:51], v[248:249], v[46:47] op_sel_hi:[1,0,1]
	v_pk_fma_f32 v[52:53], v[52:53], v[248:249], v[48:49] op_sel_hi:[1,0,1]
	v_pk_mul_f32 v[166:167], v[54:55], s[100:101] op_sel_hi:[1,0]
	v_pk_mul_f32 v[168:169], v[56:57], s[100:101] op_sel_hi:[1,0]
	v_pk_mul_f32 v[170:171], v[50:51], s[100:101] op_sel_hi:[1,0]
	v_pk_mul_f32 v[172:173], v[52:53], s[100:101] op_sel_hi:[1,0]
	v_exp_f32_e32 v166, v166
	v_exp_f32_e32 v167, v167
	v_exp_f32_e32 v168, v168
	v_exp_f32_e32 v169, v169
	v_exp_f32_e32 v170, v170
	v_exp_f32_e32 v171, v171
	v_exp_f32_e32 v172, v172
	v_exp_f32_e32 v173, v173
	v_pk_add_f32 v[166:167], v[166:167], 1.0 op_sel_hi:[1,0]
	v_pk_add_f32 v[168:169], v[168:169], 1.0 op_sel_hi:[1,0]
	v_pk_add_f32 v[170:171], v[170:171], 1.0 op_sel_hi:[1,0]
	v_pk_add_f32 v[172:173], v[172:173], 1.0 op_sel_hi:[1,0]
	v_rcp_f32_e32 v166, v166
	v_rcp_f32_e32 v167, v167
	v_rcp_f32_e32 v168, v168
	v_rcp_f32_e32 v169, v169
	v_rcp_f32_e32 v170, v170
	v_rcp_f32_e32 v171, v171
	v_rcp_f32_e32 v172, v172
	v_rcp_f32_e32 v173, v173
	v_pk_mul_f32 v[54:55], v[54:55], v[166:167]
	v_pk_mul_f32 v[56:57], v[56:57], v[168:169]
	v_pk_mul_f32 v[50:51], v[50:51], v[170:171]
	v_pk_mul_f32 v[52:53], v[52:53], v[172:173]
	v_cvt_pk_bf16_f32 v166, v54, v55
	v_cvt_pk_bf16_f32 v167, v56, v57
	v_cvt_pk_bf16_f32 v168, v50, v51
	v_cvt_pk_bf16_f32 v169, v52, v53
	global_store_dwordx4 v178, v[166:169], s[46:47] offset:256
	s_nop 1
	s_add_u32 s46, s48, 0xdc000
	s_addc_u32 s47, s49, 0
	v_pk_fma_f32 v[42:43], v[42:43], v[248:249], v[22:23] op_sel:[0,1,0]
	v_pk_fma_f32 v[44:45], v[44:45], v[248:249], v[24:25] op_sel:[0,1,0]
	v_pk_fma_f32 v[34:35], v[34:35], v[248:249], v[30:31] op_sel:[0,1,0]
	v_pk_fma_f32 v[36:37], v[36:37], v[248:249], v[32:33] op_sel:[0,1,0]
	v_pk_mul_f32 v[166:167], v[42:43], s[100:101] op_sel_hi:[1,0]
	v_pk_mul_f32 v[168:169], v[44:45], s[100:101] op_sel_hi:[1,0]
	v_pk_mul_f32 v[170:171], v[34:35], s[100:101] op_sel_hi:[1,0]
	v_pk_mul_f32 v[172:173], v[36:37], s[100:101] op_sel_hi:[1,0]
	v_exp_f32_e32 v166, v166
	v_exp_f32_e32 v167, v167
	v_exp_f32_e32 v168, v168
	v_exp_f32_e32 v169, v169
	v_exp_f32_e32 v170, v170
	v_exp_f32_e32 v171, v171
	v_exp_f32_e32 v172, v172
	v_exp_f32_e32 v173, v173
	v_pk_add_f32 v[166:167], v[166:167], 1.0 op_sel_hi:[1,0]
	v_pk_add_f32 v[168:169], v[168:169], 1.0 op_sel_hi:[1,0]
	v_pk_add_f32 v[170:171], v[170:171], 1.0 op_sel_hi:[1,0]
	v_pk_add_f32 v[172:173], v[172:173], 1.0 op_sel_hi:[1,0]
	v_rcp_f32_e32 v166, v166
	v_rcp_f32_e32 v167, v167
	v_rcp_f32_e32 v168, v168
	v_rcp_f32_e32 v169, v169
	v_rcp_f32_e32 v170, v170
	v_rcp_f32_e32 v171, v171
	v_rcp_f32_e32 v172, v172
	v_rcp_f32_e32 v173, v173
	v_pk_mul_f32 v[42:43], v[42:43], v[166:167]
	v_pk_mul_f32 v[44:45], v[44:45], v[168:169]
	v_pk_mul_f32 v[34:35], v[34:35], v[170:171]
	v_pk_mul_f32 v[36:37], v[36:37], v[172:173]
	v_cvt_pk_bf16_f32 v166, v42, v43
	v_cvt_pk_bf16_f32 v167, v44, v45
	v_cvt_pk_bf16_f32 v168, v34, v35
	v_cvt_pk_bf16_f32 v169, v36, v37
	global_store_dwordx4 v178, v[166:169], s[46:47] offset:0
	s_nop 1
	v_pk_fma_f32 v[26:27], v[26:27], v[248:249], v[38:39] op_sel:[0,1,0]
	v_pk_fma_f32 v[28:29], v[28:29], v[248:249], v[40:41] op_sel:[0,1,0]
	v_pk_fma_f32 v[18:19], v[18:19], v[248:249], v[46:47] op_sel:[0,1,0]
	v_pk_fma_f32 v[20:21], v[20:21], v[248:249], v[48:49] op_sel:[0,1,0]
	v_pk_mul_f32 v[166:167], v[26:27], s[100:101] op_sel_hi:[1,0]
	v_pk_mul_f32 v[168:169], v[28:29], s[100:101] op_sel_hi:[1,0]
	v_pk_mul_f32 v[170:171], v[18:19], s[100:101] op_sel_hi:[1,0]
	v_pk_mul_f32 v[172:173], v[20:21], s[100:101] op_sel_hi:[1,0]
	v_exp_f32_e32 v166, v166
	v_exp_f32_e32 v167, v167
	v_exp_f32_e32 v168, v168
	v_exp_f32_e32 v169, v169
	v_exp_f32_e32 v170, v170
	v_exp_f32_e32 v171, v171
	v_exp_f32_e32 v172, v172
	v_exp_f32_e32 v173, v173
	v_pk_add_f32 v[166:167], v[166:167], 1.0 op_sel_hi:[1,0]
	v_pk_add_f32 v[168:169], v[168:169], 1.0 op_sel_hi:[1,0]
	v_pk_add_f32 v[170:171], v[170:171], 1.0 op_sel_hi:[1,0]
	v_pk_add_f32 v[172:173], v[172:173], 1.0 op_sel_hi:[1,0]
	v_rcp_f32_e32 v166, v166
	v_rcp_f32_e32 v167, v167
	v_rcp_f32_e32 v168, v168
	v_rcp_f32_e32 v169, v169
	v_rcp_f32_e32 v170, v170
	v_rcp_f32_e32 v171, v171
	v_rcp_f32_e32 v172, v172
	v_rcp_f32_e32 v173, v173
	v_pk_mul_f32 v[26:27], v[26:27], v[166:167]
	v_pk_mul_f32 v[28:29], v[28:29], v[168:169]
	v_pk_mul_f32 v[18:19], v[18:19], v[170:171]
	v_pk_mul_f32 v[20:21], v[20:21], v[172:173]
	v_cvt_pk_bf16_f32 v166, v26, v27
	v_cvt_pk_bf16_f32 v167, v28, v29
	v_cvt_pk_bf16_f32 v168, v18, v19
	v_cvt_pk_bf16_f32 v169, v20, v21
; DEV float silu_f(float x) { return x * __builtin_amdgcn_rcpf(1.f + __expf(-x)); }
; DEV float gelu_f(float x) { const float t = 1.5957691216f * (x + 0.044715f * x * x * x); return x * __builtin_amdgcn_rcpf(1.f + __expf(-t)); }
; DEV u32x4 pack8(const float (&f)[8]) { u32x4 w; w.x = cvt_pk_bf16(f[0], f[1]); w.y = cvt_pk_bf16(f[2], f[3]); w.z = cvt_pk_bf16(f[4], f[5]); w.w = cvt_pk_bf16(f[6], f[7]); return w; }
;     DEV void operator()(const f32x4 (&acc)[2][2][4][2], const Unit& u, int wr, int wc, int fr, int fq) const {
;     ...
;         for (int ai = 0; ai < 2; ++ai)
; #pragma unroll
;             for (int m = 0; m < 4; ++m) {
;                 const int row = row0 + ai * 128 + m * 16; float ss = 0.f; const float rstd = rstd8[ai * 4 + m];
; #pragma unroll
;                 for (int bj = 0; bj < 2; ++bj) {
;                     float v[8];
; #pragma unroll
;                     for (int n = 0; n < 2; ++n)
; #pragma unroll
;                         for (int j = 0; j < 4; ++j) { float x = acc[ai][bj][m][n][j] * rstd + sw[bj][n][j]; if (act == 1) x = silu_f(x); else if (act == 2) x = gelu_f(x); v[4 * n + j] = x; ss += x * x; }
;                     *(u32x4*)(Z + (size_t)row * ZW + col0 + bj * 128) = pack8(v);
	global_store_dwordx4 v178, v[166:169], s[46:47] offset:256
	s_nop 1
	s_add_u32 s46, s48, 0xf2000
	s_addc_u32 s47, s49, 0
	v_pk_fma_f32 v[14:15], v[14:15], v[250:251], v[22:23] op_sel_hi:[1,0,1]
	v_pk_fma_f32 v[16:17], v[16:17], v[250:251], v[24:25] op_sel_hi:[1,0,1]
	v_pk_fma_f32 v[10:11], v[10:11], v[250:251], v[30:31] op_sel_hi:[1,0,1]
	v_pk_fma_f32 v[12:13], v[12:13], v[250:251], v[32:33] op_sel_hi:[1,0,1]
	v_pk_mul_f32 v[166:167], v[14:15], s[100:101] op_sel_hi:[1,0]
	v_pk_mul_f32 v[168:169], v[16:17], s[100:101] op_sel_hi:[1,0]
	v_pk_mul_f32 v[170:171], v[10:11], s[100:101] op_sel_hi:[1,0]
	v_pk_mul_f32 v[172:173], v[12:13], s[100:101] op_sel_hi:[1,0]
	v_exp_f32_e32 v166, v166
	v_exp_f32_e32 v167, v167
	v_exp_f32_e32 v168, v168
	v_exp_f32_e32 v169, v169
	v_exp_f32_e32 v170, v170
	v_exp_f32_e32 v171, v171
	v_exp_f32_e32 v172, v172
	v_exp_f32_e32 v173, v173
	v_pk_add_f32 v[166:167], v[166:167], 1.0 op_sel_hi:[1,0]
	v_pk_add_f32 v[168:169], v[168:169], 1.0 op_sel_hi:[1,0]
	v_pk_add_f32 v[170:171], v[170:171], 1.0 op_sel_hi:[1,0]
	v_pk_add_f32 v[172:173], v[172:173], 1.0 op_sel_hi:[1,0]
	v_rcp_f32_e32 v166, v166
	v_rcp_f32_e32 v167, v167
	v_rcp_f32_e32 v168, v168
	v_rcp_f32_e32 v169, v169
	v_rcp_f32_e32 v170, v170
	v_rcp_f32_e32 v171, v171
	v_rcp_f32_e32 v172, v172
	v_rcp_f32_e32 v173, v173
	v_pk_mul_f32 v[14:15], v[14:15], v[166:167]
	v_pk_mul_f32 v[16:17], v[16:17], v[168:169]
	v_pk_mul_f32 v[10:11], v[10:11], v[170:171]
	v_pk_mul_f32 v[12:13], v[12:13], v[172:173]
	v_cvt_pk_bf16_f32 v166, v14, v15
	v_cvt_pk_bf16_f32 v167, v16, v17
	v_cvt_pk_bf16_f32 v168, v10, v11
	v_cvt_pk_bf16_f32 v169, v12, v13
	global_store_dwordx4 v178, v[166:169], s[46:47] offset:0
	s_nop 1
	v_pk_fma_f32 v[6:7], v[6:7], v[250:251], v[38:39] op_sel_hi:[1,0,1]
	v_pk_fma_f32 v[8:9], v[8:9], v[250:251], v[40:41] op_sel_hi:[1,0,1]
	v_pk_fma_f32 v[2:3], v[2:3], v[250:251], v[46:47] op_sel_hi:[1,0,1]
	v_pk_fma_f32 v[4:5], v[4:5], v[250:251], v[48:49] op_sel_hi:[1,0,1]
	v_pk_mul_f32 v[166:167], v[6:7], s[100:101] op_sel_hi:[1,0]
	v_pk_mul_f32 v[168:169], v[8:9], s[100:101] op_sel_hi:[1,0]
	v_pk_mul_f32 v[170:171], v[2:3], s[100:101] op_sel_hi:[1,0]
	v_pk_mul_f32 v[172:173], v[4:5], s[100:101] op_sel_hi:[1,0]
	v_exp_f32_e32 v166, v166
	v_exp_f32_e32 v167, v167
	v_exp_f32_e32 v168, v168
	v_exp_f32_e32 v169, v169
	v_exp_f32_e32 v170, v170
	v_exp_f32_e32 v171, v171
	v_exp_f32_e32 v172, v172
	v_exp_f32_e32 v173, v173
	v_pk_add_f32 v[166:167], v[166:167], 1.0 op_sel_hi:[1,0]
	v_pk_add_f32 v[168:169], v[168:169], 1.0 op_sel_hi:[1,0]
	v_pk_add_f32 v[170:171], v[170:171], 1.0 op_sel_hi:[1,0]
	v_pk_add_f32 v[172:173], v[172:173], 1.0 op_sel_hi:[1,0]
	v_rcp_f32_e32 v166, v166
	v_rcp_f32_e32 v167, v167
	v_rcp_f32_e32 v168, v168
	v_rcp_f32_e32 v169, v169
	v_rcp_f32_e32 v170, v170
	v_rcp_f32_e32 v171, v171
	v_rcp_f32_e32 v172, v172
	v_rcp_f32_e32 v173, v173
	v_pk_mul_f32 v[6:7], v[6:7], v[166:167]
	v_pk_mul_f32 v[8:9], v[8:9], v[168:169]
	v_pk_mul_f32 v[2:3], v[2:3], v[170:171]
	v_pk_mul_f32 v[4:5], v[4:5], v[172:173]
	v_cvt_pk_bf16_f32 v166, v6, v7
	v_cvt_pk_bf16_f32 v167, v8, v9
	v_cvt_pk_bf16_f32 v168, v2, v3
	v_cvt_pk_bf16_f32 v169, v4, v5
	global_store_dwordx4 v178, v[166:169], s[46:47] offset:256
	s_nop 1
	s_branch .Lp5_done
.Lp5_act0:
	v_pk_fma_f32 v[142:143], v[142:143], v[242:243], v[22:23] op_sel:[0,1,0]
	v_pk_fma_f32 v[144:145], v[144:145], v[242:243], v[24:25] op_sel:[0,1,0]
	v_pk_fma_f32 v[138:139], v[138:139], v[242:243], v[30:31] op_sel:[0,1,0]
	v_pk_fma_f32 v[140:141], v[140:141], v[242:243], v[32:33] op_sel:[0,1,0]
	v_cvt_pk_bf16_f32 v166, v142, v143
	v_cvt_pk_bf16_f32 v167, v144, v145
	v_cvt_pk_bf16_f32 v168, v138, v139
	v_cvt_pk_bf16_f32 v169, v140, v141
	global_store_dwordx4 v178, v[166:169], s[48:49] offset:0
	s_nop 1
	v_pk_fma_f32 v[134:135], v[134:135], v[242:243], v[38:39] op_sel:[0,1,0]
	v_pk_fma_f32 v[136:137], v[136:137], v[242:243], v[40:41] op_sel:[0,1,0]
	v_pk_fma_f32 v[130:131], v[130:131], v[242:243], v[46:47] op_sel:[0,1,0]
	v_pk_fma_f32 v[132:133], v[132:133], v[242:243], v[48:49] op_sel:[0,1,0]
	v_cvt_pk_bf16_f32 v166, v134, v135
	v_cvt_pk_bf16_f32 v167, v136, v137
	v_cvt_pk_bf16_f32 v168, v130, v131
	v_cvt_pk_bf16_f32 v169, v132, v133
	global_store_dwordx4 v178, v[166:169], s[48:49] offset:256
	s_nop 1
	s_add_u32 s46, s48, 0x16000
	s_addc_u32 s47, s49, 0
	v_pk_fma_f32 v[126:127], v[126:127], v[244:245], v[22:23] op_sel_hi:[1,0,1]
	v_pk_fma_f32 v[128:129], v[128:129], v[244:245], v[24:25] op_sel_hi:[1,0,1]
	v_pk_fma_f32 v[122:123], v[122:123], v[244:245], v[30:31] op_sel_hi:[1,0,1]
	v_pk_fma_f32 v[124:125], v[124:125], v[244:245], v[32:33] op_sel_hi:[1,0,1]
	v_cvt_pk_bf16_f32 v166, v126, v127
	v_cvt_pk_bf16_f32 v167, v128, v129
	v_cvt_pk_bf16_f32 v168, v122, v123
	v_cvt_pk_bf16_f32 v169, v124, v125
	global_store_dwordx4 v178, v[166:169], s[46:47] offset:0
	s_nop 1
	v_pk_fma_f32 v[118:119], v[118:119], v[244:245], v[38:39] op_sel_hi:[1,0,1]
	v_pk_fma_f32 v[120:121], v[120:121], v[244:245], v[40:41] op_sel_hi:[1,0,1]
	v_pk_fma_f32 v[114:115], v[114:115], v[244:245], v[46:47] op_sel_hi:[1,0,1]
	v_pk_fma_f32 v[116:117], v[116:117], v[244:245], v[48:49] op_sel_hi:[1,0,1]
	v_cvt_pk_bf16_f32 v166, v118, v119
	v_cvt_pk_bf16_f32 v167, v120, v121
	v_cvt_pk_bf16_f32 v168, v114, v115
	v_cvt_pk_bf16_f32 v169, v116, v117
	global_store_dwordx4 v178, v[166:169], s[46:47] offset:256
	s_nop 1
	s_add_u32 s46, s48, 0x2c000
	s_addc_u32 s47, s49, 0
	v_pk_fma_f32 v[110:111], v[110:111], v[244:245], v[22:23] op_sel:[0,1,0]
	v_pk_fma_f32 v[112:113], v[112:113], v[244:245], v[24:25] op_sel:[0,1,0]
	v_pk_fma_f32 v[106:107], v[106:107], v[244:245], v[30:31] op_sel:[0,1,0]
; DEV float silu_f(float x) { return x * __builtin_amdgcn_rcpf(1.f + __expf(-x)); }
; DEV float gelu_f(float x) { const float t = 1.5957691216f * (x + 0.044715f * x * x * x); return x * __builtin_amdgcn_rcpf(1.f + __expf(-t)); }
; DEV u32x4 pack8(const float (&f)[8]) { u32x4 w; w.x = cvt_pk_bf16(f[0], f[1]); w.y = cvt_pk_bf16(f[2], f[3]); w.z = cvt_pk_bf16(f[4], f[5]); w.w = cvt_pk_bf16(f[6], f[7]); return w; }
;     DEV void operator()(const f32x4 (&acc)[2][2][4][2], const Unit& u, int wr, int wc, int fr, int fq) const {
;     ...
;         for (int ai = 0; ai < 2; ++ai)
; #pragma unroll
;             for (int m = 0; m < 4; ++m) {
;                 const int row = row0 + ai * 128 + m * 16; float ss = 0.f; const float rstd = rstd8[ai * 4 + m];
; #pragma unroll
;                 for (int bj = 0; bj < 2; ++bj) {
;                     float v[8];
; #pragma unroll
;                     for (int n = 0; n < 2; ++n)
; #pragma unroll
;                         for (int j = 0; j < 4; ++j) { float x = acc[ai][bj][m][n][j] * rstd + sw[bj][n][j]; if (act == 1) x = silu_f(x); else if (act == 2) x = gelu_f(x); v[4 * n + j] = x; ss += x * x; }
;                     *(u32x4*)(Z + (size_t)row * ZW + col0 + bj * 128) = pack8(v);
	v_pk_fma_f32 v[108:109], v[108:109], v[244:245], v[32:33] op_sel:[0,1,0]
	v_cvt_pk_bf16_f32 v166, v110, v111
	v_cvt_pk_bf16_f32 v167, v112, v113
	v_cvt_pk_bf16_f32 v168, v106, v107
	v_cvt_pk_bf16_f32 v169, v108, v109
	global_store_dwordx4 v178, v[166:169], s[46:47] offset:0
	s_nop 1
	v_pk_fma_f32 v[102:103], v[102:103], v[244:245], v[38:39] op_sel:[0,1,0]
	v_pk_fma_f32 v[104:105], v[104:105], v[244:245], v[40:41] op_sel:[0,1,0]
	v_pk_fma_f32 v[98:99], v[98:99], v[244:245], v[46:47] op_sel:[0,1,0]
	v_pk_fma_f32 v[100:101], v[100:101], v[244:245], v[48:49] op_sel:[0,1,0]
	v_cvt_pk_bf16_f32 v166, v102, v103
	v_cvt_pk_bf16_f32 v167, v104, v105
	v_cvt_pk_bf16_f32 v168, v98, v99
	v_cvt_pk_bf16_f32 v169, v100, v101
	global_store_dwordx4 v178, v[166:169], s[46:47] offset:256
	s_nop 1
	s_add_u32 s46, s48, 0x42000
	s_addc_u32 s47, s49, 0
	v_pk_fma_f32 v[94:95], v[94:95], v[246:247], v[22:23] op_sel_hi:[1,0,1]
	v_pk_fma_f32 v[96:97], v[96:97], v[246:247], v[24:25] op_sel_hi:[1,0,1]
	v_pk_fma_f32 v[90:91], v[90:91], v[246:247], v[30:31] op_sel_hi:[1,0,1]
	v_pk_fma_f32 v[92:93], v[92:93], v[246:247], v[32:33] op_sel_hi:[1,0,1]
	v_cvt_pk_bf16_f32 v166, v94, v95
	v_cvt_pk_bf16_f32 v167, v96, v97
	v_cvt_pk_bf16_f32 v168, v90, v91
	v_cvt_pk_bf16_f32 v169, v92, v93
	global_store_dwordx4 v178, v[166:169], s[46:47] offset:0
	s_nop 1
	v_pk_fma_f32 v[86:87], v[86:87], v[246:247], v[38:39] op_sel_hi:[1,0,1]
	v_pk_fma_f32 v[88:89], v[88:89], v[246:247], v[40:41] op_sel_hi:[1,0,1]
	v_pk_fma_f32 v[82:83], v[82:83], v[246:247], v[46:47] op_sel_hi:[1,0,1]
	v_pk_fma_f32 v[84:85], v[84:85], v[246:247], v[48:49] op_sel_hi:[1,0,1]
	v_cvt_pk_bf16_f32 v166, v86, v87
	v_cvt_pk_bf16_f32 v167, v88, v89
	v_cvt_pk_bf16_f32 v168, v82, v83
	v_cvt_pk_bf16_f32 v169, v84, v85
	global_store_dwordx4 v178, v[166:169], s[46:47] offset:256
	s_nop 1
	s_add_u32 s46, s48, 0xb0000
	s_addc_u32 s47, s49, 0
	v_pk_fma_f32 v[78:79], v[78:79], v[246:247], v[22:23] op_sel:[0,1,0]
	v_pk_fma_f32 v[80:81], v[80:81], v[246:247], v[24:25] op_sel:[0,1,0]
	v_pk_fma_f32 v[74:75], v[74:75], v[246:247], v[30:31] op_sel:[0,1,0]
	v_pk_fma_f32 v[76:77], v[76:77], v[246:247], v[32:33] op_sel:[0,1,0]
	v_cvt_pk_bf16_f32 v166, v78, v79
	v_cvt_pk_bf16_f32 v167, v80, v81
	v_cvt_pk_bf16_f32 v168, v74, v75
	v_cvt_pk_bf16_f32 v169, v76, v77
	global_store_dwordx4 v178, v[166:169], s[46:47] offset:0
	s_nop 1
	v_pk_fma_f32 v[70:71], v[70:71], v[246:247], v[38:39] op_sel:[0,1,0]
	v_pk_fma_f32 v[72:73], v[72:73], v[246:247], v[40:41] op_sel:[0,1,0]
	v_pk_fma_f32 v[66:67], v[66:67], v[246:247], v[46:47] op_sel:[0,1,0]
	v_pk_fma_f32 v[68:69], v[68:69], v[246:247], v[48:49] op_sel:[0,1,0]
	v_cvt_pk_bf16_f32 v166, v70, v71
	v_cvt_pk_bf16_f32 v167, v72, v73
	v_cvt_pk_bf16_f32 v168, v66, v67
	v_cvt_pk_bf16_f32 v169, v68, v69
	global_store_dwordx4 v178, v[166:169], s[46:47] offset:256
	s_nop 1
	s_add_u32 s46, s48, 0xc6000
	s_addc_u32 s47, s49, 0
	v_pk_fma_f32 v[62:63], v[62:63], v[248:249], v[22:23] op_sel_hi:[1,0,1]
	v_pk_fma_f32 v[64:65], v[64:65], v[248:249], v[24:25] op_sel_hi:[1,0,1]
	v_pk_fma_f32 v[58:59], v[58:59], v[248:249], v[30:31] op_sel_hi:[1,0,1]
	v_pk_fma_f32 v[60:61], v[60:61], v[248:249], v[32:33] op_sel_hi:[1,0,1]
	v_cvt_pk_bf16_f32 v166, v62, v63
	v_cvt_pk_bf16_f32 v167, v64, v65
	v_cvt_pk_bf16_f32 v168, v58, v59
	v_cvt_pk_bf16_f32 v169, v60, v61
	global_store_dwordx4 v178, v[166:169], s[46:47] offset:0
	s_nop 1
	v_pk_fma_f32 v[54:55], v[54:55], v[248:249], v[38:39] op_sel_hi:[1,0,1]
	v_pk_fma_f32 v[56:57], v[56:57], v[248:249], v[40:41] op_sel_hi:[1,0,1]
	v_pk_fma_f32 v[50:51], v[50:51], v[248:249], v[46:47] op_sel_hi:[1,0,1]
	v_pk_fma_f32 v[52:53], v[52:53], v[248:249], v[48:49] op_sel_hi:[1,0,1]
	v_cvt_pk_bf16_f32 v166, v54, v55
	v_cvt_pk_bf16_f32 v167, v56, v57
	v_cvt_pk_bf16_f32 v168, v50, v51
	v_cvt_pk_bf16_f32 v169, v52, v53
	global_store_dwordx4 v178, v[166:169], s[46:47] offset:256
	s_nop 1
	s_add_u32 s46, s48, 0xdc000
	s_addc_u32 s47, s49, 0
	v_pk_fma_f32 v[42:43], v[42:43], v[248:249], v[22:23] op_sel:[0,1,0]
	v_pk_fma_f32 v[44:45], v[44:45], v[248:249], v[24:25] op_sel:[0,1,0]
	v_pk_fma_f32 v[34:35], v[34:35], v[248:249], v[30:31] op_sel:[0,1,0]
	v_pk_fma_f32 v[36:37], v[36:37], v[248:249], v[32:33] op_sel:[0,1,0]
	v_cvt_pk_bf16_f32 v166, v42, v43
	v_cvt_pk_bf16_f32 v167, v44, v45
	v_cvt_pk_bf16_f32 v168, v34, v35
	v_cvt_pk_bf16_f32 v169, v36, v37
	global_store_dwordx4 v178, v[166:169], s[46:47] offset:0
	s_nop 1
	v_pk_fma_f32 v[26:27], v[26:27], v[248:249], v[38:39] op_sel:[0,1,0]
	v_pk_fma_f32 v[28:29], v[28:29], v[248:249], v[40:41] op_sel:[0,1,0]
	v_pk_fma_f32 v[18:19], v[18:19], v[248:249], v[46:47] op_sel:[0,1,0]
	v_pk_fma_f32 v[20:21], v[20:21], v[248:249], v[48:49] op_sel:[0,1,0]
	v_cvt_pk_bf16_f32 v166, v26, v27
	v_cvt_pk_bf16_f32 v167, v28, v29
	v_cvt_pk_bf16_f32 v168, v18, v19
	v_cvt_pk_bf16_f32 v169, v20, v21
	global_store_dwordx4 v178, v[166:169], s[46:47] offset:256
	s_nop 1
	s_add_u32 s46, s48, 0xf2000
	s_addc_u32 s47, s49, 0
	v_pk_fma_f32 v[14:15], v[14:15], v[250:251], v[22:23] op_sel_hi:[1,0,1]
	v_pk_fma_f32 v[16:17], v[16:17], v[250:251], v[24:25] op_sel_hi:[1,0,1]
	v_pk_fma_f32 v[10:11], v[10:11], v[250:251], v[30:31] op_sel_hi:[1,0,1]
	v_pk_fma_f32 v[12:13], v[12:13], v[250:251], v[32:33] op_sel_hi:[1,0,1]
	v_cvt_pk_bf16_f32 v166, v14, v15
	v_cvt_pk_bf16_f32 v167, v16, v17
	v_cvt_pk_bf16_f32 v168, v10, v11
	v_cvt_pk_bf16_f32 v169, v12, v13
	global_store_dwordx4 v178, v[166:169], s[46:47] offset:0
	s_nop 1
	v_pk_fma_f32 v[6:7], v[6:7], v[250:251], v[38:39] op_sel_hi:[1,0,1]
	v_pk_fma_f32 v[8:9], v[8:9], v[250:251], v[40:41] op_sel_hi:[1,0,1]
	v_pk_fma_f32 v[2:3], v[2:3], v[250:251], v[46:47] op_sel_hi:[1,0,1]
	v_pk_fma_f32 v[4:5], v[4:5], v[250:251], v[48:49] op_sel_hi:[1,0,1]
	v_cvt_pk_bf16_f32 v166, v6, v7
	v_cvt_pk_bf16_f32 v167, v8, v9
	v_cvt_pk_bf16_f32 v168, v2, v3
	v_cvt_pk_bf16_f32 v169, v4, v5
	global_store_dwordx4 v178, v[166:169], s[46:47] offset:256
	s_nop 1

; DEV u32x4 pack8(const float (&f)[8]) { u32x4 w; w.x = cvt_pk_bf16(f[0], f[1]); w.y = cvt_pk_bf16(f[2], f[3]); w.z = cvt_pk_bf16(f[4], f[5]); w.w = cvt_pk_bf16(f[6], f[7]); return w; }
; DEV float silu_f(float x) { return x * __builtin_amdgcn_rcpf(1.f + __expf(-x)); }
; DEV void row_rstd8(const float* rs, int row0, int fq, float (&rstd)[8]) {
;     f32x4 p[8];
; #pragma unroll
;     for (int i = 0; i < 8; ++i) p[i] = *(const f32x4*)(rs + (size_t)(row0 + (i >> 2) * 128 + (i & 3) * 16) * 16 + fq * 4);
; #pragma unroll
;     for (int i = 0; i < 8; ++i) { float s = (p[i].x + p[i].y) + (p[i].z + p[i].w); s += __shfl_xor(s, 16); s += __shfl_xor(s, 32); rstd[i] = rsqrtf(s * (1.f / D) + EPS); }
; }
;     DEV void operator()(const f32x4 (&acc)[2][2][4][2], const Unit& u, int wr, int wc, int fr, int fq) const {
;         asm volatile("" : "+v"(fr), "+v"(fq));
;         const int row0 = u.pm * 256 + wr * 64 + fr, col0 = u.pn * 128 + wc * 32 + 8 * fq;
;         f32x4 sg[2], su[2];
;         if (FUSED) { const int b = u.pm >> 4; const float* sp = shw + (size_t)b * NFF2 + u.pn * 256 + wc * 32 + 8 * fq;
;             sg[0] = *(const f32x4*)sp; sg[1] = *(const f32x4*)(sp + 4); su[0] = *(const f32x4*)(sp + 128); su[1] = *(const f32x4*)(sp + 132); }
;         float rstd8[8];
;         if (FUSED) row_rstd8(rs, row0, fq, rstd8);
; #pragma unroll
;         for (int ai = 0; ai < 2; ++ai)
; #pragma unroll
;             for (int m = 0; m < 4; ++m) {
;                 const int row = row0 + ai * 128 + m * 16;
;                 const float rstd = FUSED ? rstd8[ai * 4 + m] : 1.f;
;                 float h[8];
; #pragma unroll
;                 for (int n = 0; n < 2; ++n)
; #pragma unroll
;                     for (int j = 0; j < 4; ++j) { float g = acc[ai][0][m][n][j], up = acc[ai][1][m][n][j]; if (FUSED) { g = g * rstd + sg[n][j]; up = up * rstd + su[n][j]; } h[4 * n + j] = silu_f(g) * up; }
;                 *(u32x4*)(H + (size_t)row * DFF + col0) = pack8(h);
;             }
.LBB0_1898:
	s_waitcnt vmcnt(8)
	v_mov_b32_e32 v200, 0x358637bd
	s_mov_b32 s6, 0x3a800000
	v_fma_f32 v243, v243, s6, v200
	v_fma_f32 v244, v244, s6, v200
	v_fma_f32 v245, v245, s6, v200
	v_fma_f32 v246, v246, s6, v200
	v_fma_f32 v247, v247, s6, v200
	v_fma_f32 v248, v248, s6, v200
	v_fma_f32 v249, v249, s6, v200
	v_fma_f32 v250, v250, s6, v200
	v_rsq_f32_e32 v243, v243
	v_rsq_f32_e32 v244, v244
	v_rsq_f32_e32 v245, v245
	v_rsq_f32_e32 v246, v246
	v_rsq_f32_e32 v247, v247
	v_rsq_f32_e32 v248, v248
	v_rsq_f32_e32 v249, v249
	v_rsq_f32_e32 v250, v250
	s_lshl_b32 s7, s44, 4
	s_lshl_b32 s6, s45, 3
	s_add_u32 s7, s7, s6
	s_add_u32 s7, s7, 0x20000
	v_lshl_add_u32 v201, v191, 2, s7
	ds_write_b32 v201, v251
	v_lshl_add_u32 v202, v171, 5, s7
	s_lshl_b32 s23, s0, 8
	s_add_u32 s23, s23, s44
	s_lshl_b32 s6, s1, 7
	s_or_b32 s6, s6, s45
	v_add_u32_e32 v203, s23, v147
	v_mul_u32_u24_e32 v204, 0x1600, v203
	v_lshl_add_u32 v205, v171, 3, s6
	v_lshl_add_u32 v204, v205, 1, v204
	s_waitcnt lgkmcnt(0)
	ds_read_b128 v[130:133], v202
	ds_read_b128 v[134:137], v202 offset:16
	ds_read_b128 v[138:141], v202 offset:128
	ds_read_b128 v[142:145], v202 offset:144
	s_waitcnt lgkmcnt(0)
	s_mov_b32 s6, 0xbfb8aa3b
	v_pk_fma_f32 v[126:127], v[126:127], v[242:243], v[130:131] op_sel:[0,1,0]
	v_pk_fma_f32 v[128:129], v[128:129], v[242:243], v[132:133] op_sel:[0,1,0]
	v_pk_fma_f32 v[122:123], v[122:123], v[242:243], v[134:135] op_sel:[0,1,0]
	v_pk_fma_f32 v[124:125], v[124:125], v[242:243], v[136:137] op_sel:[0,1,0]
	v_pk_mul_f32 v[192:193], v[126:127], s[6:7] op_sel_hi:[1,0]
	v_pk_mul_f32 v[194:195], v[128:129], s[6:7] op_sel_hi:[1,0]
	v_pk_mul_f32 v[196:197], v[122:123], s[6:7] op_sel_hi:[1,0]
	v_pk_mul_f32 v[198:199], v[124:125], s[6:7] op_sel_hi:[1,0]
	v_exp_f32_e32 v192, v192
	v_exp_f32_e32 v193, v193
	v_exp_f32_e32 v194, v194
	v_exp_f32_e32 v195, v195
	v_exp_f32_e32 v196, v196
	v_exp_f32_e32 v197, v197
	v_exp_f32_e32 v198, v198
	v_exp_f32_e32 v199, v199
	v_pk_fma_f32 v[118:119], v[118:119], v[242:243], v[138:139] op_sel:[0,1,0]
	v_pk_fma_f32 v[120:121], v[120:121], v[242:243], v[140:141] op_sel:[0,1,0]
	v_pk_fma_f32 v[114:115], v[114:115], v[242:243], v[142:143] op_sel:[0,1,0]
	v_pk_fma_f32 v[116:117], v[116:117], v[242:243], v[144:145] op_sel:[0,1,0]
	v_pk_add_f32 v[192:193], v[192:193], 1.0 op_sel_hi:[1,0]
	v_pk_add_f32 v[194:195], v[194:195], 1.0 op_sel_hi:[1,0]
	v_pk_add_f32 v[196:197], v[196:197], 1.0 op_sel_hi:[1,0]
	v_pk_add_f32 v[198:199], v[198:199], 1.0 op_sel_hi:[1,0]
	v_rcp_f32_e32 v192, v192
	v_rcp_f32_e32 v193, v193
	v_rcp_f32_e32 v194, v194
	v_rcp_f32_e32 v195, v195
	v_rcp_f32_e32 v196, v196
	v_rcp_f32_e32 v197, v197
	v_rcp_f32_e32 v198, v198
	v_rcp_f32_e32 v199, v199
	v_pk_mul_f32 v[126:127], v[126:127], v[118:119]
	v_pk_mul_f32 v[128:129], v[128:129], v[120:121]
	v_pk_mul_f32 v[122:123], v[122:123], v[114:115]
	v_pk_mul_f32 v[124:125], v[124:125], v[116:117]
	v_pk_mul_f32 v[126:127], v[126:127], v[192:193]
	v_pk_mul_f32 v[128:129], v[128:129], v[194:195]
	v_pk_mul_f32 v[122:123], v[122:123], v[196:197]
	v_pk_mul_f32 v[124:125], v[124:125], v[198:199]
	v_cvt_pk_bf16_f32 v118, v126, v127
	v_cvt_pk_bf16_f32 v119, v128, v129
	v_cvt_pk_bf16_f32 v120, v122, v123
	v_cvt_pk_bf16_f32 v121, v124, v125
	global_store_dwordx4 v204, v[118:121], s[56:57]
	v_pk_fma_f32 v[110:111], v[110:111], v[244:245], v[130:131] op_sel_hi:[1,0,1]
	v_pk_fma_f32 v[112:113], v[112:113], v[244:245], v[132:133] op_sel_hi:[1,0,1]
	v_pk_fma_f32 v[106:107], v[106:107], v[244:245], v[134:135] op_sel_hi:[1,0,1]
	v_pk_fma_f32 v[108:109], v[108:109], v[244:245], v[136:137] op_sel_hi:[1,0,1]
	v_pk_mul_f32 v[192:193], v[110:111], s[6:7] op_sel_hi:[1,0]
	v_pk_mul_f32 v[194:195], v[112:113], s[6:7] op_sel_hi:[1,0]
	v_pk_mul_f32 v[196:197], v[106:107], s[6:7] op_sel_hi:[1,0]
	v_pk_mul_f32 v[198:199], v[108:109], s[6:7] op_sel_hi:[1,0]
	v_exp_f32_e32 v192, v192
	v_exp_f32_e32 v193, v193
	v_exp_f32_e32 v194, v194
	v_exp_f32_e32 v195, v195
	v_exp_f32_e32 v196, v196
	v_exp_f32_e32 v197, v197
	v_exp_f32_e32 v198, v198
	v_exp_f32_e32 v199, v199
	v_pk_fma_f32 v[102:103], v[102:103], v[244:245], v[138:139] op_sel_hi:[1,0,1]
	v_pk_fma_f32 v[104:105], v[104:105], v[244:245], v[140:141] op_sel_hi:[1,0,1]
	v_pk_fma_f32 v[98:99], v[98:99], v[244:245], v[142:143] op_sel_hi:[1,0,1]
	v_pk_fma_f32 v[100:101], v[100:101], v[244:245], v[144:145] op_sel_hi:[1,0,1]
	v_pk_add_f32 v[192:193], v[192:193], 1.0 op_sel_hi:[1,0]
	v_pk_add_f32 v[194:195], v[194:195], 1.0 op_sel_hi:[1,0]
	v_pk_add_f32 v[196:197], v[196:197], 1.0 op_sel_hi:[1,0]
	v_pk_add_f32 v[198:199], v[198:199], 1.0 op_sel_hi:[1,0]
	v_rcp_f32_e32 v192, v192
	v_rcp_f32_e32 v193, v193
	v_rcp_f32_e32 v194, v194
	v_rcp_f32_e32 v195, v195
	v_rcp_f32_e32 v196, v196
	v_rcp_f32_e32 v197, v197
	v_rcp_f32_e32 v198, v198
	v_rcp_f32_e32 v199, v199
	v_pk_mul_f32 v[110:111], v[110:111], v[102:103]
	v_pk_mul_f32 v[112:113], v[112:113], v[104:105]
	v_pk_mul_f32 v[106:107], v[106:107], v[98:99]
	v_pk_mul_f32 v[108:109], v[108:109], v[100:101]
	v_pk_mul_f32 v[110:111], v[110:111], v[192:193]
	v_pk_mul_f32 v[112:113], v[112:113], v[194:195]
	v_pk_mul_f32 v[106:107], v[106:107], v[196:197]
	v_pk_mul_f32 v[108:109], v[108:109], v[198:199]
	v_cvt_pk_bf16_f32 v102, v110, v111
	v_cvt_pk_bf16_f32 v103, v112, v113
	v_cvt_pk_bf16_f32 v104, v106, v107
	v_cvt_pk_bf16_f32 v105, v108, v109
	s_add_u32 s98, s56, 0x16000
	s_addc_u32 s99, s57, 0
	global_store_dwordx4 v204, v[102:105], s[98:99]
	v_pk_fma_f32 v[94:95], v[94:95], v[244:245], v[130:131] op_sel:[0,1,0]
	v_pk_fma_f32 v[96:97], v[96:97], v[244:245], v[132:133] op_sel:[0,1,0]
	v_pk_fma_f32 v[90:91], v[90:91], v[244:245], v[134:135] op_sel:[0,1,0]
; DEV u32x4 pack8(const float (&f)[8]) { u32x4 w; w.x = cvt_pk_bf16(f[0], f[1]); w.y = cvt_pk_bf16(f[2], f[3]); w.z = cvt_pk_bf16(f[4], f[5]); w.w = cvt_pk_bf16(f[6], f[7]); return w; }
; DEV float silu_f(float x) { return x * __builtin_amdgcn_rcpf(1.f + __expf(-x)); }
;     DEV void operator()(const f32x4 (&acc)[2][2][4][2], const Unit& u, int wr, int wc, int fr, int fq) const {
;     ...
; #pragma unroll
;         for (int ai = 0; ai < 2; ++ai)
; #pragma unroll
;             for (int m = 0; m < 4; ++m) {
;                 const int row = row0 + ai * 128 + m * 16;
;                 const float rstd = FUSED ? rstd8[ai * 4 + m] : 1.f;
;                 float h[8];
; #pragma unroll
;                 for (int n = 0; n < 2; ++n)
; #pragma unroll
;                     for (int j = 0; j < 4; ++j) { float g = acc[ai][0][m][n][j], up = acc[ai][1][m][n][j]; if (FUSED) { g = g * rstd + sg[n][j]; up = up * rstd + su[n][j]; } h[4 * n + j] = silu_f(g) * up; }
;                 *(u32x4*)(H + (size_t)row * DFF + col0) = pack8(h);
;             }
	v_pk_fma_f32 v[92:93], v[92:93], v[244:245], v[136:137] op_sel:[0,1,0]
	v_pk_mul_f32 v[192:193], v[94:95], s[6:7] op_sel_hi:[1,0]
	v_pk_mul_f32 v[194:195], v[96:97], s[6:7] op_sel_hi:[1,0]
	v_pk_mul_f32 v[196:197], v[90:91], s[6:7] op_sel_hi:[1,0]
	v_pk_mul_f32 v[198:199], v[92:93], s[6:7] op_sel_hi:[1,0]
	v_exp_f32_e32 v192, v192
	v_exp_f32_e32 v193, v193
	v_exp_f32_e32 v194, v194
	v_exp_f32_e32 v195, v195
	v_exp_f32_e32 v196, v196
	v_exp_f32_e32 v197, v197
	v_exp_f32_e32 v198, v198
	v_exp_f32_e32 v199, v199
	v_pk_fma_f32 v[86:87], v[86:87], v[244:245], v[138:139] op_sel:[0,1,0]
	v_pk_fma_f32 v[88:89], v[88:89], v[244:245], v[140:141] op_sel:[0,1,0]
	v_pk_fma_f32 v[82:83], v[82:83], v[244:245], v[142:143] op_sel:[0,1,0]
	v_pk_fma_f32 v[84:85], v[84:85], v[244:245], v[144:145] op_sel:[0,1,0]
	v_pk_add_f32 v[192:193], v[192:193], 1.0 op_sel_hi:[1,0]
	v_pk_add_f32 v[194:195], v[194:195], 1.0 op_sel_hi:[1,0]
	v_pk_add_f32 v[196:197], v[196:197], 1.0 op_sel_hi:[1,0]
	v_pk_add_f32 v[198:199], v[198:199], 1.0 op_sel_hi:[1,0]
	v_rcp_f32_e32 v192, v192
	v_rcp_f32_e32 v193, v193
	v_rcp_f32_e32 v194, v194
	v_rcp_f32_e32 v195, v195
	v_rcp_f32_e32 v196, v196
	v_rcp_f32_e32 v197, v197
	v_rcp_f32_e32 v198, v198
	v_rcp_f32_e32 v199, v199
	v_pk_mul_f32 v[94:95], v[94:95], v[86:87]
	v_pk_mul_f32 v[96:97], v[96:97], v[88:89]
	v_pk_mul_f32 v[90:91], v[90:91], v[82:83]
	v_pk_mul_f32 v[92:93], v[92:93], v[84:85]
	v_pk_mul_f32 v[94:95], v[94:95], v[192:193]
	v_pk_mul_f32 v[96:97], v[96:97], v[194:195]
	v_pk_mul_f32 v[90:91], v[90:91], v[196:197]
	v_pk_mul_f32 v[92:93], v[92:93], v[198:199]
	v_cvt_pk_bf16_f32 v86, v94, v95
	v_cvt_pk_bf16_f32 v87, v96, v97
	v_cvt_pk_bf16_f32 v88, v90, v91
	v_cvt_pk_bf16_f32 v89, v92, v93
	s_add_u32 s98, s56, 0x2c000
	s_addc_u32 s99, s57, 0
	global_store_dwordx4 v204, v[86:89], s[98:99]
	v_pk_fma_f32 v[78:79], v[78:79], v[246:247], v[130:131] op_sel_hi:[1,0,1]
	v_pk_fma_f32 v[80:81], v[80:81], v[246:247], v[132:133] op_sel_hi:[1,0,1]
	v_pk_fma_f32 v[74:75], v[74:75], v[246:247], v[134:135] op_sel_hi:[1,0,1]
	v_pk_fma_f32 v[76:77], v[76:77], v[246:247], v[136:137] op_sel_hi:[1,0,1]
	v_pk_mul_f32 v[192:193], v[78:79], s[6:7] op_sel_hi:[1,0]
	v_pk_mul_f32 v[194:195], v[80:81], s[6:7] op_sel_hi:[1,0]
	v_pk_mul_f32 v[196:197], v[74:75], s[6:7] op_sel_hi:[1,0]
	v_pk_mul_f32 v[198:199], v[76:77], s[6:7] op_sel_hi:[1,0]
	v_exp_f32_e32 v192, v192
	v_exp_f32_e32 v193, v193
	v_exp_f32_e32 v194, v194
	v_exp_f32_e32 v195, v195
	v_exp_f32_e32 v196, v196
	v_exp_f32_e32 v197, v197
	v_exp_f32_e32 v198, v198
	v_exp_f32_e32 v199, v199
	v_pk_fma_f32 v[70:71], v[70:71], v[246:247], v[138:139] op_sel_hi:[1,0,1]
	v_pk_fma_f32 v[72:73], v[72:73], v[246:247], v[140:141] op_sel_hi:[1,0,1]
	v_pk_fma_f32 v[66:67], v[66:67], v[246:247], v[142:143] op_sel_hi:[1,0,1]
	v_pk_fma_f32 v[68:69], v[68:69], v[246:247], v[144:145] op_sel_hi:[1,0,1]
	v_pk_add_f32 v[192:193], v[192:193], 1.0 op_sel_hi:[1,0]
	v_pk_add_f32 v[194:195], v[194:195], 1.0 op_sel_hi:[1,0]
	v_pk_add_f32 v[196:197], v[196:197], 1.0 op_sel_hi:[1,0]
	v_pk_add_f32 v[198:199], v[198:199], 1.0 op_sel_hi:[1,0]
	v_rcp_f32_e32 v192, v192
	v_rcp_f32_e32 v193, v193
	v_rcp_f32_e32 v194, v194
	v_rcp_f32_e32 v195, v195
	v_rcp_f32_e32 v196, v196
	v_rcp_f32_e32 v197, v197
	v_rcp_f32_e32 v198, v198
	v_rcp_f32_e32 v199, v199
	v_pk_mul_f32 v[78:79], v[78:79], v[70:71]
	v_pk_mul_f32 v[80:81], v[80:81], v[72:73]
	v_pk_mul_f32 v[74:75], v[74:75], v[66:67]
	v_pk_mul_f32 v[76:77], v[76:77], v[68:69]
	v_pk_mul_f32 v[78:79], v[78:79], v[192:193]
	v_pk_mul_f32 v[80:81], v[80:81], v[194:195]
	v_pk_mul_f32 v[74:75], v[74:75], v[196:197]
	v_pk_mul_f32 v[76:77], v[76:77], v[198:199]
	v_cvt_pk_bf16_f32 v70, v78, v79
	v_cvt_pk_bf16_f32 v71, v80, v81
	v_cvt_pk_bf16_f32 v72, v74, v75
	v_cvt_pk_bf16_f32 v73, v76, v77
	s_add_u32 s98, s56, 0x42000
	s_addc_u32 s99, s57, 0
	global_store_dwordx4 v204, v[70:73], s[98:99]
	v_pk_fma_f32 v[62:63], v[62:63], v[246:247], v[130:131] op_sel:[0,1,0]
	v_pk_fma_f32 v[64:65], v[64:65], v[246:247], v[132:133] op_sel:[0,1,0]
	v_pk_fma_f32 v[58:59], v[58:59], v[246:247], v[134:135] op_sel:[0,1,0]
	v_pk_fma_f32 v[60:61], v[60:61], v[246:247], v[136:137] op_sel:[0,1,0]
	v_pk_mul_f32 v[192:193], v[62:63], s[6:7] op_sel_hi:[1,0]
	v_pk_mul_f32 v[194:195], v[64:65], s[6:7] op_sel_hi:[1,0]
	v_pk_mul_f32 v[196:197], v[58:59], s[6:7] op_sel_hi:[1,0]
	v_pk_mul_f32 v[198:199], v[60:61], s[6:7] op_sel_hi:[1,0]
	v_exp_f32_e32 v192, v192
	v_exp_f32_e32 v193, v193
	v_exp_f32_e32 v194, v194
	v_exp_f32_e32 v195, v195
	v_exp_f32_e32 v196, v196
	v_exp_f32_e32 v197, v197
	v_exp_f32_e32 v198, v198
	v_exp_f32_e32 v199, v199
	v_pk_fma_f32 v[54:55], v[54:55], v[246:247], v[138:139] op_sel:[0,1,0]
	v_pk_fma_f32 v[56:57], v[56:57], v[246:247], v[140:141] op_sel:[0,1,0]
	v_pk_fma_f32 v[50:51], v[50:51], v[246:247], v[142:143] op_sel:[0,1,0]
	v_pk_fma_f32 v[52:53], v[52:53], v[246:247], v[144:145] op_sel:[0,1,0]
	v_pk_add_f32 v[192:193], v[192:193], 1.0 op_sel_hi:[1,0]
	v_pk_add_f32 v[194:195], v[194:195], 1.0 op_sel_hi:[1,0]
	v_pk_add_f32 v[196:197], v[196:197], 1.0 op_sel_hi:[1,0]
	v_pk_add_f32 v[198:199], v[198:199], 1.0 op_sel_hi:[1,0]
	v_rcp_f32_e32 v192, v192
	v_rcp_f32_e32 v193, v193
	v_rcp_f32_e32 v194, v194
	v_rcp_f32_e32 v195, v195
	v_rcp_f32_e32 v196, v196
	v_rcp_f32_e32 v197, v197
	v_rcp_f32_e32 v198, v198
	v_rcp_f32_e32 v199, v199
	v_pk_mul_f32 v[62:63], v[62:63], v[54:55]
	v_pk_mul_f32 v[64:65], v[64:65], v[56:57]
	v_pk_mul_f32 v[58:59], v[58:59], v[50:51]
	v_pk_mul_f32 v[60:61], v[60:61], v[52:53]
	v_pk_mul_f32 v[62:63], v[62:63], v[192:193]
	v_pk_mul_f32 v[64:65], v[64:65], v[194:195]
; #define PG8_BAR __builtin_amdgcn_s_barrier()
; DEV float silu_f(float x) { return x * __builtin_amdgcn_rcpf(1.f + __expf(-x)); }
; DEV u32x4 pack8(const float (&f)[8]) { u32x4 w; w.x = cvt_pk_bf16(f[0], f[1]); w.y = cvt_pk_bf16(f[2], f[3]); w.z = cvt_pk_bf16(f[4], f[5]); w.w = cvt_pk_bf16(f[6], f[7]); return w; }
; template <class Epi, class Sched, bool ALIGN_EPI = false, bool SP2 = false>
; __device__ __forceinline__ void gemm_phase(PG8_LAS unsigned char* lds, const Gemm g, const Sched& S, const Epi& E) {
;     ...
;         if (!has_next) break;
; #pragma unroll
;         for (int a = 0; a < 2; ++a)
; #pragma unroll
;             for (int b = 0; b < 2; ++b)
; #pragma unroll
;                 for (int m = 0; m < 4; ++m)
; #pragma unroll
;                     for (int n = 0; n < 2; ++n) acc[a][b][m][n] = (f32x4){0.f, 0.f, 0.f, 0.f};
;         cur = nxt; cA = nA; cB = nB; ++ui;
;         if constexpr (ALIGN_EPI) { if (wr == 1) PG8_BAR; }
;     DEV void operator()(const f32x4 (&acc)[2][2][4][2], const Unit& u, int wr, int wc, int fr, int fq) const {
;     ...
; #pragma unroll
;         for (int ai = 0; ai < 2; ++ai)
; #pragma unroll
;             for (int m = 0; m < 4; ++m) {
;                 const int row = row0 + ai * 128 + m * 16;
;                 const float rstd = FUSED ? rstd8[ai * 4 + m] : 1.f;
;                 float h[8];
; #pragma unroll
;                 for (int n = 0; n < 2; ++n)
; #pragma unroll
;                     for (int j = 0; j < 4; ++j) { float g = acc[ai][0][m][n][j], up = acc[ai][1][m][n][j]; if (FUSED) { g = g * rstd + sg[n][j]; up = up * rstd + su[n][j]; } h[4 * n + j] = silu_f(g) * up; }
;                 *(u32x4*)(H + (size_t)row * DFF + col0) = pack8(h);
;             }
	v_pk_mul_f32 v[58:59], v[58:59], v[196:197]
	v_pk_mul_f32 v[60:61], v[60:61], v[198:199]
	v_cvt_pk_bf16_f32 v54, v62, v63
	v_cvt_pk_bf16_f32 v55, v64, v65
	v_cvt_pk_bf16_f32 v56, v58, v59
	v_cvt_pk_bf16_f32 v57, v60, v61
	s_add_u32 s98, s56, 0xb0000
	s_addc_u32 s99, s57, 0
	global_store_dwordx4 v204, v[54:57], s[98:99]
	v_pk_fma_f32 v[46:47], v[46:47], v[248:249], v[130:131] op_sel_hi:[1,0,1]
	v_pk_fma_f32 v[48:49], v[48:49], v[248:249], v[132:133] op_sel_hi:[1,0,1]
	v_pk_fma_f32 v[42:43], v[42:43], v[248:249], v[134:135] op_sel_hi:[1,0,1]
	v_pk_fma_f32 v[44:45], v[44:45], v[248:249], v[136:137] op_sel_hi:[1,0,1]
	v_pk_mul_f32 v[192:193], v[46:47], s[6:7] op_sel_hi:[1,0]
	v_pk_mul_f32 v[194:195], v[48:49], s[6:7] op_sel_hi:[1,0]
	v_pk_mul_f32 v[196:197], v[42:43], s[6:7] op_sel_hi:[1,0]
	v_pk_mul_f32 v[198:199], v[44:45], s[6:7] op_sel_hi:[1,0]
	v_exp_f32_e32 v192, v192
	v_exp_f32_e32 v193, v193
	v_exp_f32_e32 v194, v194
	v_exp_f32_e32 v195, v195
	v_exp_f32_e32 v196, v196
	v_exp_f32_e32 v197, v197
	v_exp_f32_e32 v198, v198
	v_exp_f32_e32 v199, v199
	v_pk_fma_f32 v[38:39], v[38:39], v[248:249], v[138:139] op_sel_hi:[1,0,1]
	v_pk_fma_f32 v[40:41], v[40:41], v[248:249], v[140:141] op_sel_hi:[1,0,1]
	v_pk_fma_f32 v[34:35], v[34:35], v[248:249], v[142:143] op_sel_hi:[1,0,1]
	v_pk_fma_f32 v[36:37], v[36:37], v[248:249], v[144:145] op_sel_hi:[1,0,1]
	v_pk_add_f32 v[192:193], v[192:193], 1.0 op_sel_hi:[1,0]
	v_pk_add_f32 v[194:195], v[194:195], 1.0 op_sel_hi:[1,0]
	v_pk_add_f32 v[196:197], v[196:197], 1.0 op_sel_hi:[1,0]
	v_pk_add_f32 v[198:199], v[198:199], 1.0 op_sel_hi:[1,0]
	v_rcp_f32_e32 v192, v192
	v_rcp_f32_e32 v193, v193
	v_rcp_f32_e32 v194, v194
	v_rcp_f32_e32 v195, v195
	v_rcp_f32_e32 v196, v196
	v_rcp_f32_e32 v197, v197
	v_rcp_f32_e32 v198, v198
	v_rcp_f32_e32 v199, v199
	v_pk_mul_f32 v[46:47], v[46:47], v[38:39]
	v_pk_mul_f32 v[48:49], v[48:49], v[40:41]
	v_pk_mul_f32 v[42:43], v[42:43], v[34:35]
	v_pk_mul_f32 v[44:45], v[44:45], v[36:37]
	v_pk_mul_f32 v[46:47], v[46:47], v[192:193]
	v_pk_mul_f32 v[48:49], v[48:49], v[194:195]
	v_pk_mul_f32 v[42:43], v[42:43], v[196:197]
	v_pk_mul_f32 v[44:45], v[44:45], v[198:199]
	v_cvt_pk_bf16_f32 v38, v46, v47
	v_cvt_pk_bf16_f32 v39, v48, v49
	v_cvt_pk_bf16_f32 v40, v42, v43
	v_cvt_pk_bf16_f32 v41, v44, v45
	s_add_u32 s98, s56, 0xc6000
	s_addc_u32 s99, s57, 0
	global_store_dwordx4 v204, v[38:41], s[98:99]
	v_pk_fma_f32 v[30:31], v[30:31], v[248:249], v[130:131] op_sel:[0,1,0]
	v_pk_fma_f32 v[32:33], v[32:33], v[248:249], v[132:133] op_sel:[0,1,0]
	v_pk_fma_f32 v[26:27], v[26:27], v[248:249], v[134:135] op_sel:[0,1,0]
	v_pk_fma_f32 v[28:29], v[28:29], v[248:249], v[136:137] op_sel:[0,1,0]
	v_pk_mul_f32 v[192:193], v[30:31], s[6:7] op_sel_hi:[1,0]
	v_pk_mul_f32 v[194:195], v[32:33], s[6:7] op_sel_hi:[1,0]
	v_pk_mul_f32 v[196:197], v[26:27], s[6:7] op_sel_hi:[1,0]
	v_pk_mul_f32 v[198:199], v[28:29], s[6:7] op_sel_hi:[1,0]
	v_exp_f32_e32 v192, v192
	v_exp_f32_e32 v193, v193
	v_exp_f32_e32 v194, v194
	v_exp_f32_e32 v195, v195
	v_exp_f32_e32 v196, v196
	v_exp_f32_e32 v197, v197
	v_exp_f32_e32 v198, v198
	v_exp_f32_e32 v199, v199
	v_pk_fma_f32 v[22:23], v[22:23], v[248:249], v[138:139] op_sel:[0,1,0]
	v_pk_fma_f32 v[24:25], v[24:25], v[248:249], v[140:141] op_sel:[0,1,0]
	v_pk_fma_f32 v[18:19], v[18:19], v[248:249], v[142:143] op_sel:[0,1,0]
	v_pk_fma_f32 v[20:21], v[20:21], v[248:249], v[144:145] op_sel:[0,1,0]
	v_pk_add_f32 v[192:193], v[192:193], 1.0 op_sel_hi:[1,0]
	v_pk_add_f32 v[194:195], v[194:195], 1.0 op_sel_hi:[1,0]
	v_pk_add_f32 v[196:197], v[196:197], 1.0 op_sel_hi:[1,0]
	v_pk_add_f32 v[198:199], v[198:199], 1.0 op_sel_hi:[1,0]
	v_rcp_f32_e32 v192, v192
	v_rcp_f32_e32 v193, v193
	v_rcp_f32_e32 v194, v194
	v_rcp_f32_e32 v195, v195
	v_rcp_f32_e32 v196, v196
	v_rcp_f32_e32 v197, v197
	v_rcp_f32_e32 v198, v198
	v_rcp_f32_e32 v199, v199
	v_pk_mul_f32 v[30:31], v[30:31], v[22:23]
	v_pk_mul_f32 v[32:33], v[32:33], v[24:25]
	v_pk_mul_f32 v[26:27], v[26:27], v[18:19]
	v_pk_mul_f32 v[28:29], v[28:29], v[20:21]
	v_pk_mul_f32 v[30:31], v[30:31], v[192:193]
	v_pk_mul_f32 v[32:33], v[32:33], v[194:195]
	v_pk_mul_f32 v[26:27], v[26:27], v[196:197]
	v_pk_mul_f32 v[28:29], v[28:29], v[198:199]
	v_cvt_pk_bf16_f32 v22, v30, v31
	v_cvt_pk_bf16_f32 v23, v32, v33
	v_cvt_pk_bf16_f32 v24, v26, v27
	v_cvt_pk_bf16_f32 v25, v28, v29
	s_add_u32 s98, s56, 0xdc000
	s_addc_u32 s99, s57, 0
	global_store_dwordx4 v204, v[22:25], s[98:99]
	v_pk_fma_f32 v[14:15], v[14:15], v[250:251], v[130:131] op_sel_hi:[1,0,1]
	v_pk_fma_f32 v[16:17], v[16:17], v[250:251], v[132:133] op_sel_hi:[1,0,1]
	v_pk_fma_f32 v[10:11], v[10:11], v[250:251], v[134:135] op_sel_hi:[1,0,1]
	v_pk_fma_f32 v[12:13], v[12:13], v[250:251], v[136:137] op_sel_hi:[1,0,1]
	v_pk_mul_f32 v[192:193], v[14:15], s[6:7] op_sel_hi:[1,0]
	v_pk_mul_f32 v[194:195], v[16:17], s[6:7] op_sel_hi:[1,0]
	v_pk_mul_f32 v[196:197], v[10:11], s[6:7] op_sel_hi:[1,0]
	v_pk_mul_f32 v[198:199], v[12:13], s[6:7] op_sel_hi:[1,0]
	v_exp_f32_e32 v192, v192
	v_exp_f32_e32 v193, v193
	v_exp_f32_e32 v194, v194
	v_exp_f32_e32 v195, v195
	v_exp_f32_e32 v196, v196
	v_exp_f32_e32 v197, v197
	v_exp_f32_e32 v198, v198
	v_exp_f32_e32 v199, v199
	v_pk_fma_f32 v[6:7], v[6:7], v[250:251], v[138:139] op_sel_hi:[1,0,1]
	v_pk_fma_f32 v[8:9], v[8:9], v[250:251], v[140:141] op_sel_hi:[1,0,1]
	v_pk_fma_f32 v[2:3], v[2:3], v[250:251], v[142:143] op_sel_hi:[1,0,1]
	v_pk_fma_f32 v[4:5], v[4:5], v[250:251], v[144:145] op_sel_hi:[1,0,1]
	v_pk_add_f32 v[192:193], v[192:193], 1.0 op_sel_hi:[1,0]
	v_pk_add_f32 v[194:195], v[194:195], 1.0 op_sel_hi:[1,0]
	v_pk_add_f32 v[196:197], v[196:197], 1.0 op_sel_hi:[1,0]
	v_pk_add_f32 v[198:199], v[198:199], 1.0 op_sel_hi:[1,0]
	v_rcp_f32_e32 v192, v192
	v_rcp_f32_e32 v193, v193
	v_rcp_f32_e32 v194, v194
	v_rcp_f32_e32 v195, v195
	v_rcp_f32_e32 v196, v196
	v_rcp_f32_e32 v197, v197
	v_rcp_f32_e32 v198, v198
	v_rcp_f32_e32 v199, v199
	v_pk_mul_f32 v[14:15], v[14:15], v[6:7]
	v_pk_mul_f32 v[16:17], v[16:17], v[8:9]
	v_pk_mul_f32 v[10:11], v[10:11], v[2:3]
	v_pk_mul_f32 v[12:13], v[12:13], v[4:5]
	v_pk_mul_f32 v[14:15], v[14:15], v[192:193]
	v_pk_mul_f32 v[16:17], v[16:17], v[194:195]
	v_pk_mul_f32 v[10:11], v[10:11], v[196:197]
	v_pk_mul_f32 v[12:13], v[12:13], v[198:199]
	v_cvt_pk_bf16_f32 v6, v14, v15
	v_cvt_pk_bf16_f32 v7, v16, v17
	v_cvt_pk_bf16_f32 v8, v10, v11
	v_cvt_pk_bf16_f32 v9, v12, v13
	s_add_u32 s98, s56, 0xf2000
	s_addc_u32 s99, s57, 0
	global_store_dwordx4 v204, v[6:9], s[98:99]
	s_andn2_b64 vcc, exec, s[4:5]
	s_mov_b64 s[0:1], -1
	s_cbranch_vccnz .LBB0_1891
	s_andn2_b64 vcc, exec, s[10:11]
	s_cbranch_vccnz .LBB0_1890
	s_barrier
	s_branch .LBB0_1890
